# hand-scheduled attention loop body, pipelined merge phase, pipelined prologue row norm
# speedup vs baseline: 1.0172x; 1.0172x over previous
.LBB0_8:
	s_lshr_b32 s30, s10, 6
	s_lshl_b32 s2, s72, 3
	s_add_i32 s76, s30, s2
	s_lshl_b32 s78, s97, 3
	s_add_u32 s74, s88, 0x6000000
	s_addc_u32 s75, s89, 0
	s_cmp_lt_i32 s90, 1
	s_cselect_b64 s[2:3], -1, 0
	s_cmp_gt_i32 s91, 0
	s_cselect_b64 s[4:5], -1, 0
	s_and_b64 s[2:3], s[2:3], s[4:5]
	s_andn2_b64 vcc, exec, s[2:3]
	s_cbranch_vccnz .LBB0_74
	s_bitcmp0_b32 s10, 6
	s_cselect_b64 s[24:25], -1, 0
	s_cmp_lt_i32 s76, 0x8000
	v_mov_b32_e32 v0, v200
	s_cselect_b64 s[4:5], -1, 0
	s_and_b64 vcc, exec, s[24:25]
	v_and_b32_e32 v59, 63, v0
	v_cndmask_b32_e64 v0, 0, 1, s[4:5]
	v_cmp_ne_u32_e64 s[6:7], 1, v0
	s_cbranch_vccnz .LBB0_21
	s_and_b64 vcc, exec, s[6:7]
	s_cbranch_vccnz .LBB0_21
	s_waitcnt lgkmcnt(0)
	v_and_b32_e32 v147, 63, v200
	v_lshlrev_b32_e32 v144, 4, v147
	v_lshlrev_b32_e32 v145, 3, v147
	v_mov_b32_e32 v150, 0x358637bd
	v_readlane_b32 s8, v248, 2
	v_readlane_b32 s9, v248, 3
	v_readlane_b32 s16, v248, 6
	v_readlane_b32 s17, v248, 7
	s_mov_b32 s14, 0x3a800000
	s_lshl_b32 s12, s78, 12
	s_lshl_b32 s13, s78, 11
	s_mov_b32 s4, s76
	s_mov_b32 s5, s76
	s_lshr_b32 s19, s76, 20
	s_lshl_b32 s18, s76, 12
	s_add_u32 s8, s8, s18
	s_addc_u32 s9, s9, s19
	s_lshr_b32 s19, s76, 21
	s_lshl_b32 s18, s76, 11
	s_add_u32 s10, s74, s18
	s_addc_u32 s11, s75, s19
	global_load_dwordx4 v[128:131], v144, s[16:17]
	global_load_dwordx4 v[132:135], v144, s[16:17] offset:1024
	global_load_dwordx4 v[136:139], v144, s[16:17] offset:2048
	global_load_dwordx4 v[140:143], v144, s[16:17] offset:3072
	global_load_dwordx4 v[64:67], v144, s[8:9] nt
	global_load_dwordx4 v[68:71], v144, s[8:9] offset:1024 nt
	global_load_dwordx4 v[72:75], v144, s[8:9] offset:2048 nt
	global_load_dwordx4 v[76:79], v144, s[8:9] offset:3072 nt
	s_add_u32 s8, s8, s12
	s_addc_u32 s9, s9, 0
	s_add_i32 s4, s4, s78
	s_cmp_lt_i32 s4, 0x8000
	s_cbranch_scc0 .Lrw_filla
	global_load_dwordx4 v[80:83], v144, s[8:9] nt
	global_load_dwordx4 v[84:87], v144, s[8:9] offset:1024 nt
	global_load_dwordx4 v[88:91], v144, s[8:9] offset:2048 nt
	global_load_dwordx4 v[92:95], v144, s[8:9] offset:3072 nt
	s_add_u32 s8, s8, s12
	s_addc_u32 s9, s9, 0
	s_add_i32 s4, s4, s78
	s_cmp_lt_i32 s4, 0x8000
	s_cbranch_scc0 .Lrw_filla
	global_load_dwordx4 v[96:99], v144, s[8:9] nt
	global_load_dwordx4 v[100:103], v144, s[8:9] offset:1024 nt
	global_load_dwordx4 v[104:107], v144, s[8:9] offset:2048 nt
	global_load_dwordx4 v[108:111], v144, s[8:9] offset:3072 nt
	s_add_u32 s8, s8, s12
	s_addc_u32 s9, s9, 0
	s_add_i32 s4, s4, s78
	s_cmp_lt_i32 s4, 0x8000
	s_cbranch_scc0 .Lrw_filla
	global_load_dwordx4 v[112:115], v144, s[8:9] nt
	global_load_dwordx4 v[116:119], v144, s[8:9] offset:1024 nt
	global_load_dwordx4 v[120:123], v144, s[8:9] offset:2048 nt
	global_load_dwordx4 v[124:127], v144, s[8:9] offset:3072 nt
	s_add_u32 s8, s8, s12
	s_addc_u32 s9, s9, 0
	s_add_i32 s4, s4, s78
.Lrw_filla:
	s_mov_b32 s19, 1
.Lrw_loopa:
	s_mul_i32 s15, s78, 3
	s_add_i32 s15, s15, s5
	s_cmp_lt_i32 s15, 0x8000
	s_cbranch_scc1 .Lrw_f0a
	s_waitcnt vmcnt(0)
	s_branch .Lrw_c0a
.Lrw_f0a:
	s_cmp_eq_u32 s19, 1
	s_cbranch_scc1 .Lrw_g0a
	s_waitcnt vmcnt(24)
	s_branch .Lrw_c0a
.Lrw_g0a:
	s_waitcnt vmcnt(12)
.Lrw_c0a:
	v_mul_f32_e32 v146, v64, v64
	v_fmac_f32_e32 v146, v65, v65
	v_fmac_f32_e32 v146, v66, v66
	v_fmac_f32_e32 v146, v67, v67
	v_fmac_f32_e32 v146, v68, v68
	v_fmac_f32_e32 v146, v69, v69
	v_fmac_f32_e32 v146, v70, v70
	v_fmac_f32_e32 v146, v71, v71
	v_fmac_f32_e32 v146, v72, v72
	v_fmac_f32_e32 v146, v73, v73
	v_fmac_f32_e32 v146, v74, v74
	v_fmac_f32_e32 v146, v75, v75
	v_fmac_f32_e32 v146, v76, v76
	v_fmac_f32_e32 v146, v77, v77
	v_fmac_f32_e32 v146, v78, v78
	v_fmac_f32_e32 v146, v79, v79
	v_mul_f32_e32 v64, v64, v128
	v_mul_f32_e32 v65, v65, v129
	v_add_f32_dpp v146, v146, v146 quad_perm:[1,0,3,2] row_mask:0xf bank_mask:0xf
	v_mul_f32_e32 v66, v66, v130
	v_mul_f32_e32 v67, v67, v131
	v_add_f32_dpp v146, v146, v146 quad_perm:[2,3,0,1] row_mask:0xf bank_mask:0xf
	v_mul_f32_e32 v68, v68, v132
	v_mul_f32_e32 v69, v69, v133
	v_add_f32_dpp v146, v146, v146 row_ror:4 row_mask:0xf bank_mask:0xf
	v_mul_f32_e32 v70, v70, v134
	v_mul_f32_e32 v71, v71, v135
	v_add_f32_dpp v146, v146, v146 row_ror:8 row_mask:0xf bank_mask:0xf
	v_mul_f32_e32 v72, v72, v136
	v_mul_f32_e32 v73, v73, v137
	v_mov_b32_e32 v147, v146
	v_mul_f32_e32 v74, v74, v138
	v_mul_f32_e32 v75, v75, v139
	v_permlane16_swap_b32_e32 v146, v147
	v_add_f32_e32 v146, v146, v147
	v_mov_b32_e32 v147, v146
	v_mul_f32_e32 v76, v76, v140
	v_mul_f32_e32 v77, v77, v141
	v_permlane32_swap_b32_e32 v146, v147
	v_add_f32_e32 v146, v146, v147
	v_mul_f32_e32 v78, v78, v142
	v_mul_f32_e32 v79, v79, v143
	v_fma_f32 v146, v146, s14, v150
	v_rsq_f32_e32 v148, v146
	v_mul_f32_e32 v146, 0.5, v146
	s_nop 0
	v_mul_f32_e32 v149, v148, v148
	v_fma_f32 v149, -v146, v149, 0.5
	v_fmac_f32_e32 v148, v148, v149
	v_mul_f32_e32 v64, v64, v148
	v_mul_f32_e32 v65, v65, v148
	v_mul_f32_e32 v66, v66, v148
	v_mul_f32_e32 v67, v67, v148
	v_mul_f32_e32 v68, v68, v148
	v_mul_f32_e32 v69, v69, v148
	v_mul_f32_e32 v70, v70, v148
	v_mul_f32_e32 v71, v71, v148
	v_mul_f32_e32 v72, v72, v148
	v_mul_f32_e32 v73, v73, v148
	v_mul_f32_e32 v74, v74, v148
	v_mul_f32_e32 v75, v75, v148
	v_mul_f32_e32 v76, v76, v148
	v_mul_f32_e32 v77, v77, v148
	v_mul_f32_e32 v78, v78, v148
	v_mul_f32_e32 v79, v79, v148
	v_cvt_pk_bf16_f32 v64, v64, v65
	v_cvt_pk_bf16_f32 v65, v66, v67
	v_cvt_pk_bf16_f32 v68, v68, v69
	v_cvt_pk_bf16_f32 v69, v70, v71
	v_cvt_pk_bf16_f32 v72, v72, v73
	v_cvt_pk_bf16_f32 v73, v74, v75
	v_cvt_pk_bf16_f32 v76, v76, v77
	v_cvt_pk_bf16_f32 v77, v78, v79
	global_store_dwordx2 v145, v[64:65], s[10:11]
	global_store_dwordx2 v145, v[68:69], s[10:11] offset:512
	global_store_dwordx2 v145, v[72:73], s[10:11] offset:1024
	global_store_dwordx2 v145, v[76:77], s[10:11] offset:1536
	s_add_u32 s10, s10, s13
	s_addc_u32 s11, s11, 0
	s_cmp_lt_i32 s4, 0x8000
	s_cbranch_scc0 .Lrw_nl0a
	global_load_dwordx4 v[64:67], v144, s[8:9] nt
	global_load_dwordx4 v[68:71], v144, s[8:9] offset:1024 nt
	global_load_dwordx4 v[72:75], v144, s[8:9] offset:2048 nt
	global_load_dwordx4 v[76:79], v144, s[8:9] offset:3072 nt
	s_add_u32 s8, s8, s12
	s_addc_u32 s9, s9, 0
	s_add_i32 s4, s4, s78
.Lrw_nl0a:
	s_add_i32 s5, s5, s78
	s_cmp_lt_i32 s5, 0x8000
	s_cbranch_scc0 .LBB0_21
	s_mul_i32 s15, s78, 3
	s_add_i32 s15, s15, s5
	s_cmp_lt_i32 s15, 0x8000
	s_cbranch_scc1 .Lrw_f1a
	s_waitcnt vmcnt(0)
	s_branch .Lrw_c1a

.Lrw_g1a:
	s_waitcnt vmcnt(16)
.Lrw_c1a:
	v_mul_f32_e32 v146, v80, v80
	v_fmac_f32_e32 v146, v81, v81
	v_fmac_f32_e32 v146, v82, v82
	v_fmac_f32_e32 v146, v83, v83
	v_fmac_f32_e32 v146, v84, v84
	v_fmac_f32_e32 v146, v85, v85
	v_fmac_f32_e32 v146, v86, v86
	v_fmac_f32_e32 v146, v87, v87
	v_fmac_f32_e32 v146, v88, v88
	v_fmac_f32_e32 v146, v89, v89
	v_fmac_f32_e32 v146, v90, v90
	v_fmac_f32_e32 v146, v91, v91
	v_fmac_f32_e32 v146, v92, v92
	v_fmac_f32_e32 v146, v93, v93
	v_fmac_f32_e32 v146, v94, v94
	v_fmac_f32_e32 v146, v95, v95
	v_mul_f32_e32 v80, v80, v128
	v_mul_f32_e32 v81, v81, v129
	v_add_f32_dpp v146, v146, v146 quad_perm:[1,0,3,2] row_mask:0xf bank_mask:0xf
	v_mul_f32_e32 v82, v82, v130
	v_mul_f32_e32 v83, v83, v131
	v_add_f32_dpp v146, v146, v146 quad_perm:[2,3,0,1] row_mask:0xf bank_mask:0xf
	v_mul_f32_e32 v84, v84, v132
	v_mul_f32_e32 v85, v85, v133
	v_add_f32_dpp v146, v146, v146 row_ror:4 row_mask:0xf bank_mask:0xf
	v_mul_f32_e32 v86, v86, v134
	v_mul_f32_e32 v87, v87, v135
	v_add_f32_dpp v146, v146, v146 row_ror:8 row_mask:0xf bank_mask:0xf
	v_mul_f32_e32 v88, v88, v136
	v_mul_f32_e32 v89, v89, v137
	v_mov_b32_e32 v147, v146
	v_mul_f32_e32 v90, v90, v138
	v_mul_f32_e32 v91, v91, v139
	v_permlane16_swap_b32_e32 v146, v147
	v_add_f32_e32 v146, v146, v147
	v_mov_b32_e32 v147, v146
	v_mul_f32_e32 v92, v92, v140
	v_mul_f32_e32 v93, v93, v141
	v_permlane32_swap_b32_e32 v146, v147
	v_add_f32_e32 v146, v146, v147
	v_mul_f32_e32 v94, v94, v142
	v_mul_f32_e32 v95, v95, v143
	v_fma_f32 v146, v146, s14, v150
	v_rsq_f32_e32 v148, v146
	v_mul_f32_e32 v146, 0.5, v146
	s_nop 0
	v_mul_f32_e32 v149, v148, v148
	v_fma_f32 v149, -v146, v149, 0.5
	v_fmac_f32_e32 v148, v148, v149
	v_mul_f32_e32 v80, v80, v148
	v_mul_f32_e32 v81, v81, v148
	v_mul_f32_e32 v82, v82, v148
	v_mul_f32_e32 v83, v83, v148
	v_mul_f32_e32 v84, v84, v148
	v_mul_f32_e32 v85, v85, v148
	v_mul_f32_e32 v86, v86, v148
	v_mul_f32_e32 v87, v87, v148
	v_mul_f32_e32 v88, v88, v148
	v_mul_f32_e32 v89, v89, v148
	v_mul_f32_e32 v90, v90, v148
	v_mul_f32_e32 v91, v91, v148
	v_mul_f32_e32 v92, v92, v148
	v_mul_f32_e32 v93, v93, v148
	v_mul_f32_e32 v94, v94, v148
	v_mul_f32_e32 v95, v95, v148
	v_cvt_pk_bf16_f32 v80, v80, v81
	v_cvt_pk_bf16_f32 v81, v82, v83
	v_cvt_pk_bf16_f32 v84, v84, v85
	v_cvt_pk_bf16_f32 v85, v86, v87
	v_cvt_pk_bf16_f32 v88, v88, v89
	v_cvt_pk_bf16_f32 v89, v90, v91
	v_cvt_pk_bf16_f32 v92, v92, v93
	v_cvt_pk_bf16_f32 v93, v94, v95
	global_store_dwordx2 v145, v[80:81], s[10:11]
	global_store_dwordx2 v145, v[84:85], s[10:11] offset:512
	global_store_dwordx2 v145, v[88:89], s[10:11] offset:1024
	global_store_dwordx2 v145, v[92:93], s[10:11] offset:1536
	s_add_u32 s10, s10, s13
	s_addc_u32 s11, s11, 0
	s_cmp_lt_i32 s4, 0x8000
	s_cbranch_scc0 .Lrw_nl1a
	global_load_dwordx4 v[80:83], v144, s[8:9] nt
	global_load_dwordx4 v[84:87], v144, s[8:9] offset:1024 nt
	global_load_dwordx4 v[88:91], v144, s[8:9] offset:2048 nt
	global_load_dwordx4 v[92:95], v144, s[8:9] offset:3072 nt
	s_add_u32 s8, s8, s12
	s_addc_u32 s9, s9, 0
	s_add_i32 s4, s4, s78

.Lrw_g2a:
	s_waitcnt vmcnt(20)
.Lrw_c2a:
	v_mul_f32_e32 v146, v96, v96
	v_fmac_f32_e32 v146, v97, v97
	v_fmac_f32_e32 v146, v98, v98
	v_fmac_f32_e32 v146, v99, v99
	v_fmac_f32_e32 v146, v100, v100
	v_fmac_f32_e32 v146, v101, v101
	v_fmac_f32_e32 v146, v102, v102
	v_fmac_f32_e32 v146, v103, v103
	v_fmac_f32_e32 v146, v104, v104
	v_fmac_f32_e32 v146, v105, v105
	v_fmac_f32_e32 v146, v106, v106
	v_fmac_f32_e32 v146, v107, v107
	v_fmac_f32_e32 v146, v108, v108
	v_fmac_f32_e32 v146, v109, v109
	v_fmac_f32_e32 v146, v110, v110
	v_fmac_f32_e32 v146, v111, v111
	v_mul_f32_e32 v96, v96, v128
	v_mul_f32_e32 v97, v97, v129
	v_add_f32_dpp v146, v146, v146 quad_perm:[1,0,3,2] row_mask:0xf bank_mask:0xf
	v_mul_f32_e32 v98, v98, v130
	v_mul_f32_e32 v99, v99, v131
	v_add_f32_dpp v146, v146, v146 quad_perm:[2,3,0,1] row_mask:0xf bank_mask:0xf
	v_mul_f32_e32 v100, v100, v132
	v_mul_f32_e32 v101, v101, v133
	v_add_f32_dpp v146, v146, v146 row_ror:4 row_mask:0xf bank_mask:0xf
	v_mul_f32_e32 v102, v102, v134
	v_mul_f32_e32 v103, v103, v135
	v_add_f32_dpp v146, v146, v146 row_ror:8 row_mask:0xf bank_mask:0xf
	v_mul_f32_e32 v104, v104, v136
	v_mul_f32_e32 v105, v105, v137
	v_mov_b32_e32 v147, v146
	v_mul_f32_e32 v106, v106, v138
	v_mul_f32_e32 v107, v107, v139
	v_permlane16_swap_b32_e32 v146, v147
	v_add_f32_e32 v146, v146, v147
	v_mov_b32_e32 v147, v146
	v_mul_f32_e32 v108, v108, v140
	v_mul_f32_e32 v109, v109, v141
	v_permlane32_swap_b32_e32 v146, v147
	v_add_f32_e32 v146, v146, v147
	v_mul_f32_e32 v110, v110, v142
	v_mul_f32_e32 v111, v111, v143
	v_fma_f32 v146, v146, s14, v150
	v_rsq_f32_e32 v148, v146
	v_mul_f32_e32 v146, 0.5, v146
	s_nop 0
	v_mul_f32_e32 v149, v148, v148
	v_fma_f32 v149, -v146, v149, 0.5
	v_fmac_f32_e32 v148, v148, v149
	v_mul_f32_e32 v96, v96, v148
	v_mul_f32_e32 v97, v97, v148
	v_mul_f32_e32 v98, v98, v148
	v_mul_f32_e32 v99, v99, v148
	v_mul_f32_e32 v100, v100, v148
	v_mul_f32_e32 v101, v101, v148
	v_mul_f32_e32 v102, v102, v148
	v_mul_f32_e32 v103, v103, v148
	v_mul_f32_e32 v104, v104, v148
	v_mul_f32_e32 v105, v105, v148
	v_mul_f32_e32 v106, v106, v148
	v_mul_f32_e32 v107, v107, v148
	v_mul_f32_e32 v108, v108, v148
	v_mul_f32_e32 v109, v109, v148
	v_mul_f32_e32 v110, v110, v148
	v_mul_f32_e32 v111, v111, v148
	v_cvt_pk_bf16_f32 v96, v96, v97
	v_cvt_pk_bf16_f32 v97, v98, v99
	v_cvt_pk_bf16_f32 v100, v100, v101
	v_cvt_pk_bf16_f32 v101, v102, v103
	v_cvt_pk_bf16_f32 v104, v104, v105
	v_cvt_pk_bf16_f32 v105, v106, v107
	v_cvt_pk_bf16_f32 v108, v108, v109
	v_cvt_pk_bf16_f32 v109, v110, v111
	global_store_dwordx2 v145, v[96:97], s[10:11]
	global_store_dwordx2 v145, v[100:101], s[10:11] offset:512
	global_store_dwordx2 v145, v[104:105], s[10:11] offset:1024
	global_store_dwordx2 v145, v[108:109], s[10:11] offset:1536
	s_add_u32 s10, s10, s13
	s_addc_u32 s11, s11, 0
	s_cmp_lt_i32 s4, 0x8000
	s_cbranch_scc0 .Lrw_nl2a
	global_load_dwordx4 v[96:99], v144, s[8:9] nt
	global_load_dwordx4 v[100:103], v144, s[8:9] offset:1024 nt
	global_load_dwordx4 v[104:107], v144, s[8:9] offset:2048 nt
	global_load_dwordx4 v[108:111], v144, s[8:9] offset:3072 nt
	s_add_u32 s8, s8, s12
	s_addc_u32 s9, s9, 0
	s_add_i32 s4, s4, s78

.Lrw_f3a:
	s_waitcnt vmcnt(24)
.Lrw_c3a:
	v_mul_f32_e32 v146, v112, v112
	v_fmac_f32_e32 v146, v113, v113
	v_fmac_f32_e32 v146, v114, v114
	v_fmac_f32_e32 v146, v115, v115
	v_fmac_f32_e32 v146, v116, v116
	v_fmac_f32_e32 v146, v117, v117
	v_fmac_f32_e32 v146, v118, v118
	v_fmac_f32_e32 v146, v119, v119
	v_fmac_f32_e32 v146, v120, v120
	v_fmac_f32_e32 v146, v121, v121
	v_fmac_f32_e32 v146, v122, v122
	v_fmac_f32_e32 v146, v123, v123
	v_fmac_f32_e32 v146, v124, v124
	v_fmac_f32_e32 v146, v125, v125
	v_fmac_f32_e32 v146, v126, v126
	v_fmac_f32_e32 v146, v127, v127
	v_mul_f32_e32 v112, v112, v128
	v_mul_f32_e32 v113, v113, v129
	v_add_f32_dpp v146, v146, v146 quad_perm:[1,0,3,2] row_mask:0xf bank_mask:0xf
	v_mul_f32_e32 v114, v114, v130
	v_mul_f32_e32 v115, v115, v131
	v_add_f32_dpp v146, v146, v146 quad_perm:[2,3,0,1] row_mask:0xf bank_mask:0xf
	v_mul_f32_e32 v116, v116, v132
	v_mul_f32_e32 v117, v117, v133
	v_add_f32_dpp v146, v146, v146 row_ror:4 row_mask:0xf bank_mask:0xf
	v_mul_f32_e32 v118, v118, v134
	v_mul_f32_e32 v119, v119, v135
	v_add_f32_dpp v146, v146, v146 row_ror:8 row_mask:0xf bank_mask:0xf
	v_mul_f32_e32 v120, v120, v136
	v_mul_f32_e32 v121, v121, v137
	v_mov_b32_e32 v147, v146
	v_mul_f32_e32 v122, v122, v138
	v_mul_f32_e32 v123, v123, v139
	v_permlane16_swap_b32_e32 v146, v147
	v_add_f32_e32 v146, v146, v147
	v_mov_b32_e32 v147, v146
	v_mul_f32_e32 v124, v124, v140
	v_mul_f32_e32 v125, v125, v141
	v_permlane32_swap_b32_e32 v146, v147
	v_add_f32_e32 v146, v146, v147
	v_mul_f32_e32 v126, v126, v142
	v_mul_f32_e32 v127, v127, v143
	v_fma_f32 v146, v146, s14, v150
	v_rsq_f32_e32 v148, v146
	v_mul_f32_e32 v146, 0.5, v146
	s_nop 0
	v_mul_f32_e32 v149, v148, v148
	v_fma_f32 v149, -v146, v149, 0.5
	v_fmac_f32_e32 v148, v148, v149
	v_mul_f32_e32 v112, v112, v148
	v_mul_f32_e32 v113, v113, v148
	v_mul_f32_e32 v114, v114, v148
	v_mul_f32_e32 v115, v115, v148
	v_mul_f32_e32 v116, v116, v148
	v_mul_f32_e32 v117, v117, v148
	v_mul_f32_e32 v118, v118, v148
	v_mul_f32_e32 v119, v119, v148
	v_mul_f32_e32 v120, v120, v148
	v_mul_f32_e32 v121, v121, v148
	v_mul_f32_e32 v122, v122, v148
	v_mul_f32_e32 v123, v123, v148
	v_mul_f32_e32 v124, v124, v148
	v_mul_f32_e32 v125, v125, v148
	v_mul_f32_e32 v126, v126, v148
	v_mul_f32_e32 v127, v127, v148
	v_cvt_pk_bf16_f32 v112, v112, v113
	v_cvt_pk_bf16_f32 v113, v114, v115
	v_cvt_pk_bf16_f32 v116, v116, v117
	v_cvt_pk_bf16_f32 v117, v118, v119
	v_cvt_pk_bf16_f32 v120, v120, v121
	v_cvt_pk_bf16_f32 v121, v122, v123
	v_cvt_pk_bf16_f32 v124, v124, v125
	v_cvt_pk_bf16_f32 v125, v126, v127
	global_store_dwordx2 v145, v[112:113], s[10:11]
	global_store_dwordx2 v145, v[116:117], s[10:11] offset:512
	global_store_dwordx2 v145, v[120:121], s[10:11] offset:1024
	global_store_dwordx2 v145, v[124:125], s[10:11] offset:1536
	s_add_u32 s10, s10, s13
	s_addc_u32 s11, s11, 0
	s_cmp_lt_i32 s4, 0x8000
	s_cbranch_scc0 .Lrw_nl3a
	global_load_dwordx4 v[112:115], v144, s[8:9] nt
	global_load_dwordx4 v[116:119], v144, s[8:9] offset:1024 nt
	global_load_dwordx4 v[120:123], v144, s[8:9] offset:2048 nt
	global_load_dwordx4 v[124:127], v144, s[8:9] offset:3072 nt
	s_add_u32 s8, s8, s12
	s_addc_u32 s9, s9, 0
	s_add_i32 s4, s4, s78
.Lrw_nl3a:
	s_add_i32 s5, s5, s78
	s_cmp_lt_i32 s5, 0x8000
	s_mov_b32 s19, 0
	s_cbranch_scc1 .Lrw_loopa

.LBB0_61:
	s_and_b64 vcc, exec, s[24:25]
	s_cbranch_vccz .LBB0_73
	s_and_b64 vcc, exec, s[6:7]
	s_cbranch_vccnz .LBB0_73
	s_waitcnt lgkmcnt(0)
	v_and_b32_e32 v147, 63, v200
	v_lshlrev_b32_e32 v144, 4, v147
	v_lshlrev_b32_e32 v145, 3, v147
	v_mov_b32_e32 v150, 0x358637bd
	v_readlane_b32 s8, v248, 2
	v_readlane_b32 s9, v248, 3
	v_readlane_b32 s16, v248, 6
	v_readlane_b32 s17, v248, 7
	s_mov_b32 s14, 0x3a800000
	s_lshl_b32 s12, s78, 12
	s_lshl_b32 s13, s78, 11
	s_mov_b32 s4, s76
	s_mov_b32 s5, s76
	s_lshr_b32 s19, s76, 20
	s_lshl_b32 s18, s76, 12
	s_add_u32 s8, s8, s18
	s_addc_u32 s9, s9, s19
	s_lshr_b32 s19, s76, 21
	s_lshl_b32 s18, s76, 11
	s_add_u32 s10, s74, s18
	s_addc_u32 s11, s75, s19
	global_load_dwordx4 v[128:131], v144, s[16:17]
	global_load_dwordx4 v[132:135], v144, s[16:17] offset:1024
	global_load_dwordx4 v[136:139], v144, s[16:17] offset:2048
	global_load_dwordx4 v[140:143], v144, s[16:17] offset:3072
	global_load_dwordx4 v[64:67], v144, s[8:9] nt
	global_load_dwordx4 v[68:71], v144, s[8:9] offset:1024 nt
	global_load_dwordx4 v[72:75], v144, s[8:9] offset:2048 nt
	global_load_dwordx4 v[76:79], v144, s[8:9] offset:3072 nt
	s_add_u32 s8, s8, s12
	s_addc_u32 s9, s9, 0
	s_add_i32 s4, s4, s78
	s_cmp_lt_i32 s4, 0x8000
	s_cbranch_scc0 .Lrw_fillb
	global_load_dwordx4 v[80:83], v144, s[8:9] nt
	global_load_dwordx4 v[84:87], v144, s[8:9] offset:1024 nt
	global_load_dwordx4 v[88:91], v144, s[8:9] offset:2048 nt
	global_load_dwordx4 v[92:95], v144, s[8:9] offset:3072 nt
	s_add_u32 s8, s8, s12
	s_addc_u32 s9, s9, 0
	s_add_i32 s4, s4, s78
	s_cmp_lt_i32 s4, 0x8000
	s_cbranch_scc0 .Lrw_fillb
	global_load_dwordx4 v[96:99], v144, s[8:9] nt
	global_load_dwordx4 v[100:103], v144, s[8:9] offset:1024 nt
	global_load_dwordx4 v[104:107], v144, s[8:9] offset:2048 nt
	global_load_dwordx4 v[108:111], v144, s[8:9] offset:3072 nt
	s_add_u32 s8, s8, s12
	s_addc_u32 s9, s9, 0
	s_add_i32 s4, s4, s78
	s_cmp_lt_i32 s4, 0x8000
	s_cbranch_scc0 .Lrw_fillb
	global_load_dwordx4 v[112:115], v144, s[8:9] nt
	global_load_dwordx4 v[116:119], v144, s[8:9] offset:1024 nt
	global_load_dwordx4 v[120:123], v144, s[8:9] offset:2048 nt
	global_load_dwordx4 v[124:127], v144, s[8:9] offset:3072 nt
	s_add_u32 s8, s8, s12
	s_addc_u32 s9, s9, 0
	s_add_i32 s4, s4, s78

.LBB0_232:
	v_lshrrev_b32_e32 v5, 5, v2
	v_lshlrev_b32_e32 v6, 2, v5
	v_lshrrev_b32_e32 v4, 2, v1
	v_and_or_b32 v4, v4, 3, v6
	v_lshlrev_b32_e32 v7, 1, v1
	v_and_b32_e32 v7, 32, v7
	v_and_b32_e32 v3, 24, v3
	v_lshlrev_b32_e32 v8, 9, v1
	v_lshlrev_b32_e32 v9, 4, v1
	v_lshl_add_u32 v4, v4, 6, 0
	v_and_b32_e32 v8, 0x800, v8
	v_and_b32_e32 v10, 48, v9
	v_add3_u32 v170, v4, v7, v3
	v_and_b32_e32 v7, 0xfffff000, v9
	v_lshlrev_b32_e32 v9, 6, v165
	v_add_u32_e32 v8, 0, v8
	v_and_b32_e32 v9, 0x7c0, v9
	v_add3_u32 v7, v8, v7, v9
	v_add_u32_e32 v9, 0x200, v1
	v_ashrrev_i32_e32 v173, 3, v9
	v_lshlrev_b32_e32 v9, 4, v9
	v_lshlrev_b32_e32 v17, 6, v173
	v_and_b32_e32 v9, 0xfffff000, v9
	v_and_b32_e32 v17, 0x7c0, v17
	v_add3_u32 v9, v8, v9, v17
	v_add_u32_e32 v17, 0x400, v1
	v_ashrrev_i32_e32 v174, 3, v17
	v_lshlrev_b32_e32 v17, 4, v17
	v_lshlrev_b32_e32 v20, 6, v174
	s_lshl_b32 s7, s30, 12
	v_and_b32_e32 v17, 0xfffff000, v17
	v_and_b32_e32 v20, 0x7c0, v20
	v_writelane_b32 v248, s73, 29
	s_mov_b32 s68, s78
	s_add_i32 s0, s7, 0
	v_add3_u32 v17, v8, v17, v20
	v_add_u32_e32 v20, 0x600, v1
	v_writelane_b32 v248, s68, 30
	s_add_i32 s6, s0, 0x18000
	v_ashrrev_i32_e32 v175, 3, v20
	v_writelane_b32 v248, s69, 31
	s_mov_b32 s66, s76
	s_and_b64 s[0:1], exec, s[2:3]
	v_lshlrev_b32_e32 v20, 4, v20
	v_lshlrev_b32_e32 v23, 6, v175
	v_writelane_b32 v248, s66, 32
	s_cselect_b32 s0, 32, s5
	s_add_i32 s1, s30, 1
	v_and_b32_e32 v20, 0xfffff000, v20
	v_and_b32_e32 v23, 0x7c0, v23
	v_writelane_b32 v248, s67, 33
	s_lshl_b32 s93, s1, 5
	s_lshl_b32 s8, s1, 12
	s_add_i32 s1, s30, 2
	s_add_i32 s30, s30, 3
	v_add3_u32 v20, v8, v20, v23
	v_add_u32_e32 v23, 0x800, v1
	v_writelane_b32 v248, s0, 34
	s_lshl_b32 s9, s30, 5
	v_ashrrev_i32_e32 v176, 3, v23
	v_writelane_b32 v248, s9, 35
	s_add_i32 s10, s7, 0x4000
	v_lshlrev_b32_e32 v23, 4, v23
	v_lshlrev_b32_e32 v26, 6, v176
	v_writelane_b32 v248, s10, 36
	v_cmp_gt_u32_e64 s[10:11], 32, v2
	v_and_b32_e32 v23, 0xfffff000, v23
	v_and_b32_e32 v26, 0x7c0, v26
	v_writelane_b32 v248, s10, 37
	v_add3_u32 v23, v8, v23, v26
	v_add_u32_e32 v26, 0xa00, v1
	v_writelane_b32 v248, s11, 38
	v_ashrrev_i32_e32 v177, 3, v26
	v_and_b32_e32 v166, 31, v1
	v_and_b32_e32 v12, 7, v1
	v_bitop3_b32 v13, v164, v1, 7 bitop3:0x78
	v_xor_b32_e32 v3, v165, v1
	v_xor_b32_e32 v16, v173, v1
	v_xor_b32_e32 v19, v174, v1
	v_xor_b32_e32 v22, v175, v1
	v_xor_b32_e32 v25, v176, v1
	v_xor_b32_e32 v28, v177, v1
	v_bitop3_b32 v1, v5, v1, 7 bitop3:0x78
	v_writelane_b32 v248, s7, 39
	s_lshl_b32 s5, s1, 5
	s_lshl_b32 s1, s1, 12
	v_lshlrev_b32_e32 v14, 7, v166
	v_lshlrev_b32_e32 v178, 4, v1
	v_bitop3_b32 v1, v5, v12, 2 bitop3:0x36
	v_writelane_b32 v248, s8, 40
	s_lshl_b32 s9, s30, 12
	v_lshlrev_b32_e32 v167, 7, v164
	v_lshlrev_b32_e32 v13, 4, v13
	v_add_u32_e32 v168, s6, v14
	v_add_u32_e32 v14, 0, v14
	v_lshlrev_b32_e32 v179, 4, v1
	v_bitop3_b32 v1, v5, v12, 4 bitop3:0x36
	v_writelane_b32 v248, s1, 41
	v_add_u32_e32 v11, s6, v167
	v_add_u32_e32 v172, s6, v13
	v_lshlrev_b32_e32 v180, 4, v1
	v_bitop3_b32 v1, v5, v12, 6 bitop3:0x36
	v_add_u32_e32 v182, s7, v14
	v_writelane_b32 v248, s9, 42
	v_cmp_gt_u32_e64 s[6:7], v6, v166
	v_lshlrev_b32_e32 v181, 4, v1
	v_or_b32_e32 v1, 1, v6
	v_writelane_b32 v248, s6, 43
	v_lshlrev_b32_e32 v26, 4, v26
	v_lshlrev_b32_e32 v29, 6, v177
	v_writelane_b32 v248, s7, 44
	v_cmp_lt_u32_e64 s[6:7], v1, v166
	v_or_b32_e32 v1, 2, v6
	v_lshlrev_b32_e32 v3, 4, v3
	v_writelane_b32 v248, s6, 45
	v_lshlrev_b32_e32 v16, 4, v16
	v_lshlrev_b32_e32 v19, 4, v19
	v_writelane_b32 v248, s7, 46
	v_cmp_lt_u32_e64 s[6:7], v1, v166
	v_lshlrev_b32_e32 v22, 4, v22
	v_lshlrev_b32_e32 v25, 4, v25
	v_writelane_b32 v248, s6, 47
	v_lshlrev_b32_e32 v28, 4, v28
	v_and_b32_e32 v26, 0xfffff000, v26
	v_writelane_b32 v248, s7, 48
	v_cmp_gt_u32_e64 s[6:7], v1, v166
	v_or_b32_e32 v1, 3, v6
	v_and_b32_e32 v29, 0x7c0, v29
	v_writelane_b32 v248, s6, 49
	v_lshlrev_b32_e32 v186, 4, v12
	v_or_b32_e32 v187, 8, v164
	v_writelane_b32 v248, s7, 50
	v_cmp_lt_u32_e64 s[6:7], v1, v166
	v_or_b32_e32 v188, 16, v164
	v_or_b32_e32 v189, 24, v164
	v_writelane_b32 v248, s6, 51
	s_lshl_b32 s0, s21, 6
	v_lshlrev_b32_e32 v4, 3, v12
	v_writelane_b32 v248, s7, 52
	v_cmp_gt_u32_e64 s[6:7], v1, v166
	v_or_b32_e32 v1, 8, v6
	v_lshl_add_u32 v171, v5, 3, v168
	v_writelane_b32 v248, s6, 53
	v_lshl_add_u32 v2, v165, 7, 0
	v_and_b32_e32 v3, 0x70, v3
	v_writelane_b32 v248, s7, 54
	v_cmp_lt_u32_e64 s[6:7], v1, v166
	v_lshl_add_u32 v15, v173, 7, 0
	v_and_b32_e32 v16, 0x70, v16
	v_writelane_b32 v248, s6, 55
	v_lshl_add_u32 v18, v174, 7, 0
	v_and_b32_e32 v19, 0x70, v19
	v_writelane_b32 v248, s7, 56
	v_cmp_gt_u32_e64 s[6:7], v1, v166
	v_or_b32_e32 v1, 9, v6
	v_lshl_add_u32 v21, v175, 7, 0
	v_writelane_b32 v248, s6, 57
	v_and_b32_e32 v22, 0x70, v22
	v_lshl_add_u32 v24, v176, 7, 0
	v_writelane_b32 v248, s7, 58
	v_cmp_lt_u32_e64 s[6:7], v1, v166
	v_and_b32_e32 v25, 0x70, v25
	v_lshl_add_u32 v27, v177, 7, 0
	v_writelane_b32 v248, s6, 59
	v_and_b32_e32 v28, 0x70, v28
	v_add3_u32 v8, v8, v26, v29
	v_writelane_b32 v248, s7, 60
	v_cmp_gt_u32_e64 s[6:7], v1, v166
	v_or_b32_e32 v1, 10, v6
	v_cmp_lt_u32_e64 s[24:25], v1, v166
	v_cmp_gt_u32_e64 s[26:27], v1, v166
	v_or_b32_e32 v1, 11, v6
	v_cmp_lt_u32_e64 s[28:29], v1, v166
	v_cmp_gt_u32_e64 s[30:31], v1, v166
	v_or_b32_e32 v1, 16, v6
	v_cmp_lt_u32_e64 s[34:35], v1, v166
	v_cmp_gt_u32_e64 s[36:37], v1, v166
	v_or_b32_e32 v1, 17, v6
	v_cmp_lt_u32_e64 s[38:39], v1, v166
	v_cmp_gt_u32_e64 s[40:41], v1, v166
	v_or_b32_e32 v1, 18, v6
	v_cmp_lt_u32_e64 s[42:43], v1, v166
	v_cmp_gt_u32_e64 s[44:45], v1, v166
	v_or_b32_e32 v1, 19, v6
	v_cmp_lt_u32_e64 s[46:47], v1, v166
	v_cmp_gt_u32_e64 s[48:49], v1, v166
	v_or_b32_e32 v1, 24, v6
	v_cmp_lt_u32_e64 s[50:51], v1, v166
	v_cmp_gt_u32_e64 s[52:53], v1, v166
	v_or_b32_e32 v1, 25, v6
	v_writelane_b32 v248, s6, 61
	v_cmp_lt_u32_e64 s[54:55], v1, v166
	v_cmp_gt_u32_e64 s[56:57], v1, v166
	v_or_b32_e32 v1, 26, v6
	v_writelane_b32 v248, s7, 62
	v_cmp_lt_u32_e64 s[58:59], v1, v166
	v_cmp_gt_u32_e64 s[60:61], v1, v166
	v_or_b32_e32 v1, 27, v6
	v_add_u32_e32 v183, s8, v14
	v_add_u32_e32 v184, s1, v14
	v_add_u32_e32 v185, s9, v14
	v_cmp_lt_u32_e64 s[66:67], v6, v166
	v_cmp_lt_u32_e64 s[62:63], v1, v166
	v_cmp_gt_u32_e64 s[64:65], v1, v166
	v_xor_b32_e32 v1, 64, v186
	v_xor_b32_e32 v5, 16, v186
	v_xor_b32_e32 v6, 0x50, v186
	v_xor_b32_e32 v12, 32, v186
	v_xor_b32_e32 v14, 0x60, v186
	v_xor_b32_e32 v26, 48, v186
	v_xor_b32_e32 v29, 0x70, v186
	v_lshlrev_b32_e32 v30, 7, v187
	v_lshlrev_b32_e32 v31, 7, v188
	v_lshlrev_b32_e32 v32, 7, v189
	v_readlane_b32 s1, v248, 28
	v_or_b32_e32 v169, s33, v164
	v_mov_b32_e32 v161, 0
	s_add_i32 s14, s1, 0x58
	v_add_u32_e32 v190, v2, v3
	v_add_u32_e32 v191, v7, v10
	v_add_u32_e32 v192, v15, v16
	v_add_u32_e32 v193, v9, v10
	v_add_u32_e32 v194, v18, v19
	v_add_u32_e32 v195, v17, v10
	v_add_u32_e32 v196, v21, v22
	v_add_u32_e32 v197, v20, v10
	v_add_u32_e32 v198, v24, v25
	v_add_u32_e32 v199, v23, v10
	v_add_u32_e32 v201, v27, v28
	v_add_u32_e32 v202, v8, v10
	v_add_u32_e32 v203, v11, v13
	v_lshlrev_b32_e32 v162, 1, v0
	s_brev_b32 s15, 64
	s_lshl_b32 s94, s0, 1
	v_add_u32_e32 v204, v171, v1
	v_add_u32_e32 v205, v171, v5
	v_add_u32_e32 v206, v171, v6
	v_add_u32_e32 v207, v171, v12
	v_add_u32_e32 v208, v171, v14
	v_add_u32_e32 v209, v171, v26
	v_add_u32_e32 v210, v171, v29
	v_lshlrev_b32_e32 v160, 1, v4
	v_add_u32_e32 v211, v172, v30
	v_add_u32_e32 v212, v172, v31
	v_add_u32_e32 v213, v172, v32
	v_mov_b32_e32 v214, 0xf149f2ca
	s_mov_b32 s6, 0
	s_mov_b32 s68, 0
	v_and_b32_e32 v251, 31, v200
	v_bfe_u32 v163, v200, 5, 1
	v_lshlrev_b32_e32 v163, 2, v163
	v_sub_u32_e32 v251, v251, v163
	v_cmp_gt_i32_e64 s[24:25], v251, 0
	v_cmp_gt_i32_e64 s[26:27], v251, 1
	v_cmp_gt_i32_e64 s[28:29], v251, 2
	v_cmp_gt_i32_e64 s[30:31], v251, 3
	v_cmp_gt_i32_e64 s[34:35], v251, 8
	v_cmp_gt_i32_e64 s[36:37], v251, 9
	v_cmp_gt_i32_e64 s[38:39], v251, 10
	v_cmp_gt_i32_e64 s[40:41], v251, 11
	v_cmp_gt_i32_e64 s[42:43], v251, 16
	v_cmp_gt_i32_e64 s[44:45], v251, 17
	v_cmp_gt_i32_e64 s[46:47], v251, 18
	v_cmp_gt_i32_e64 s[48:49], v251, 19
	v_cmp_gt_i32_e64 s[50:51], v251, 24
	v_cmp_gt_i32_e64 s[52:53], v251, 25
	v_cmp_gt_i32_e64 s[54:55], v251, 26
	v_cmp_gt_i32_e64 s[56:57], v251, 27
	v_cmp_lt_i32_e64 s[58:59], v251, 0
	v_cmp_lt_i32_e64 s[60:61], v251, 8
	v_cmp_lt_i32_e64 s[62:63], v251, 16
	v_cmp_lt_i32_e64 s[64:65], v251, 24
	s_branch .LBB0_234

.LBB0_238:
	s_waitcnt vmcnt(0)
	s_barrier
	ds_write_b128 v190, v[112:115]
	ds_write_b128 v191, v[116:119] offset:49152
	ds_write_b128 v192, v[120:123]
	ds_write_b128 v193, v[124:127] offset:49152
	ds_write_b128 v194, v[132:135]
	ds_write_b128 v195, v[128:131] offset:49152
	ds_write_b128 v196, v[140:143]
	ds_write_b128 v197, v[136:139] offset:49152
	ds_write_b128 v198, v[148:151]
	ds_write_b128 v199, v[144:147] offset:49152
	ds_write_b128 v201, v[156:159]
	ds_write_b128 v202, v[152:155] offset:49152
	ds_write_b128 v203, v[96:99]
	ds_write_b128 v203, v[100:103] offset:1024
	ds_write_b128 v203, v[104:107] offset:2048
	ds_write_b128 v203, v[108:111] offset:3072
	v_add_u32_e32 v0, v168, v178
	v_add_u32_e32 v1, v168, v179
	ds_read_b128 v[216:219], v0
	ds_read_b128 v[220:223], v1
	v_add_u32_e32 v0, v168, v180
	v_add_u32_e32 v8, v168, v181
	ds_read_b128 v[224:227], v0
	ds_read_b128 v[228:231], v8
	s_add_i32 s95, s6, 1
	s_cmp_ge_i32 s95, s17
	s_waitcnt lgkmcnt(0)
	s_barrier
	s_cbranch_scc1 .LBB0_242
	s_cmp_gt_u32 s6, 7
	s_cselect_b64 s[0:1], -1, 0
	s_and_b64 s[0:1], s[2:3], s[0:1]
	s_and_b64 vcc, exec, s[0:1]
	s_mov_b32 s0, s14
	s_cbranch_vccnz .LBB0_241
	v_readlane_b32 s0, v248, 34
	s_mul_i32 s0, s95, s0
	v_readlane_b32 s1, v248, 28
	s_add_i32 s0, s0, s1

.LBB0_242:
	s_mul_hi_i32 s0, s7, 0x2aaaaaab
	s_lshr_b32 s1, s0, 31
	s_ashr_i32 s0, s0, 3
	s_add_i32 s6, s0, s1
	s_mul_i32 s0, s6, 48
	s_sub_i32 s0, s7, s0
	s_and_b32 s7, s0, 15
	s_ashr_i32 s0, s0, 4
	s_lshl_b32 s96, s0, 1
	s_lshr_b32 s1, 16, s96
	s_add_i32 s1, s1, -1
	s_and_b32 s1, s1, s7
	s_lshl_b32 s1, s1, 8
	s_sub_i32 s18, 0x7f, s1
	v_add_u32_e32 v252, v182, v178
	v_add_u32_e32 v253, v182, v179
	v_add_u32_e32 v254, v182, v180
	v_add_u32_e32 v255, v182, v181
	ds_read_b128 v[80:83], v252
	ds_read_b128 v[84:87], v253
	ds_read_b128 v[88:91], v254
	ds_read_b128 v[92:95], v255
	ds_read_b128 v[232:235], v252 offset:4096
	ds_read_b128 v[236:239], v253 offset:4096
	ds_read_b128 v[240:243], v254 offset:4096
	ds_read_b128 v[244:247], v255 offset:4096
	s_waitcnt lgkmcnt(4)
	v_mfma_f32_32x32x16_bf16 v[0:15], v[80:83], v[216:219], 0
	v_mfma_f32_32x32x16_bf16 v[0:15], v[84:87], v[220:223], v[0:15]
	v_mfma_f32_32x32x16_bf16 v[0:15], v[88:91], v[224:227], v[0:15]
	v_mfma_f32_32x32x16_bf16 v[0:15], v[92:95], v[228:231], v[0:15]
	ds_read_b128 v[80:83], v252 offset:8192
	ds_read_b128 v[84:87], v253 offset:8192
	ds_read_b128 v[88:91], v254 offset:8192
	ds_read_b128 v[92:95], v255 offset:8192
	s_waitcnt lgkmcnt(4)
	v_mfma_f32_32x32x16_bf16 v[16:31], v[232:235], v[216:219], 0
	v_mfma_f32_32x32x16_bf16 v[16:31], v[236:239], v[220:223], v[16:31]
	v_mfma_f32_32x32x16_bf16 v[16:31], v[240:243], v[224:227], v[16:31]
	v_mfma_f32_32x32x16_bf16 v[16:31], v[244:247], v[228:231], v[16:31]
	ds_read_b128 v[232:235], v252 offset:12288
	ds_read_b128 v[236:239], v253 offset:12288
	ds_read_b128 v[240:243], v254 offset:12288
	ds_read_b128 v[244:247], v255 offset:12288
	s_waitcnt lgkmcnt(4)
	v_mfma_f32_32x32x16_bf16 v[32:47], v[80:83], v[216:219], 0
	v_mfma_f32_32x32x16_bf16 v[32:47], v[84:87], v[220:223], v[32:47]
	v_mfma_f32_32x32x16_bf16 v[32:47], v[88:91], v[224:227], v[32:47]
	v_mfma_f32_32x32x16_bf16 v[32:47], v[92:95], v[228:231], v[32:47]
	ds_read_b128 v[80:83], v252 offset:16384
	ds_read_b128 v[84:87], v253 offset:16384
	ds_read_b128 v[88:91], v254 offset:16384
	ds_read_b128 v[92:95], v255 offset:16384
	s_waitcnt lgkmcnt(4)
	v_mfma_f32_32x32x16_bf16 v[48:63], v[232:235], v[216:219], 0
	v_mfma_f32_32x32x16_bf16 v[48:63], v[236:239], v[220:223], v[48:63]
	v_mfma_f32_32x32x16_bf16 v[48:63], v[240:243], v[224:227], v[48:63]
	v_mfma_f32_32x32x16_bf16 v[48:63], v[244:247], v[228:231], v[48:63]
	s_waitcnt lgkmcnt(0)
	v_mfma_f32_32x32x16_bf16 v[64:79], v[80:83], v[216:219], 0
	v_mfma_f32_32x32x16_bf16 v[64:79], v[84:87], v[220:223], v[64:79]
	v_mfma_f32_32x32x16_bf16 v[64:79], v[88:91], v[224:227], v[64:79]
	v_mfma_f32_32x32x16_bf16 v[64:79], v[92:95], v[228:231], v[64:79]
	v_readlane_b32 s12, v248, 39
	s_nop 1
	v_add_u32_e32 v252, s12, v170
	v_add_u32_e32 v253, 0x3000, v252
	v_cndmask_b32_e64 v0, v0, v214, s[24:25]
	v_cndmask_b32_e64 v1, v1, v214, s[26:27]
	v_cndmask_b32_e64 v2, v2, v214, s[28:29]
	v_cndmask_b32_e64 v3, v3, v214, s[30:31]
	v_cndmask_b32_e64 v4, v4, v214, s[34:35]
	v_cndmask_b32_e64 v5, v5, v214, s[36:37]
	v_cndmask_b32_e64 v6, v6, v214, s[38:39]
	v_cndmask_b32_e64 v7, v7, v214, s[40:41]
	v_cndmask_b32_e64 v8, v8, v214, s[42:43]
	v_cndmask_b32_e64 v9, v9, v214, s[44:45]
	v_cndmask_b32_e64 v10, v10, v214, s[46:47]
	v_cndmask_b32_e64 v11, v11, v214, s[48:49]
	v_cndmask_b32_e64 v12, v12, v214, s[50:51]
	v_cndmask_b32_e64 v13, v13, v214, s[52:53]
	v_cndmask_b32_e64 v14, v14, v214, s[54:55]
	v_cndmask_b32_e64 v15, v15, v214, s[56:57]
	s_cmp_gt_i32 s33, s18
	s_cbranch_scc1 .Lat_ex0
	v_mov_b32_e32 v0, v214
	v_mov_b32_e32 v1, v214
	v_mov_b32_e32 v2, v214
	v_mov_b32_e32 v3, v214
	v_mov_b32_e32 v4, v214
	v_mov_b32_e32 v5, v214
	v_mov_b32_e32 v6, v214
	v_mov_b32_e32 v7, v214
	v_mov_b32_e32 v8, v214
	v_mov_b32_e32 v9, v214
	v_mov_b32_e32 v10, v214
	v_mov_b32_e32 v11, v214
	v_mov_b32_e32 v12, v214
	v_mov_b32_e32 v13, v214
	v_mov_b32_e32 v14, v214
	v_mov_b32_e32 v15, v214
.Lat_ex0:
	s_add_i32 s10, s33, 32
	s_cmp_gt_i32 s10, s18
	s_cbranch_scc1 .Lat_ex1
	v_mov_b32_e32 v16, v214
	v_mov_b32_e32 v17, v214
	v_mov_b32_e32 v18, v214
	v_mov_b32_e32 v19, v214
	v_mov_b32_e32 v20, v214
	v_mov_b32_e32 v21, v214
	v_mov_b32_e32 v22, v214
	v_mov_b32_e32 v23, v214
	v_mov_b32_e32 v24, v214
	v_mov_b32_e32 v25, v214
	v_mov_b32_e32 v26, v214
	v_mov_b32_e32 v27, v214
	v_mov_b32_e32 v28, v214
	v_mov_b32_e32 v29, v214
	v_mov_b32_e32 v30, v214
	v_mov_b32_e32 v31, v214
.Lat_ex1:
	s_add_i32 s10, s33, 64
	s_cmp_gt_i32 s10, s18
	s_cbranch_scc1 .Lat_ex2
	v_mov_b32_e32 v32, v214
	v_mov_b32_e32 v33, v214
	v_mov_b32_e32 v34, v214
	v_mov_b32_e32 v35, v214
	v_mov_b32_e32 v36, v214
	v_mov_b32_e32 v37, v214
	v_mov_b32_e32 v38, v214
	v_mov_b32_e32 v39, v214
	v_mov_b32_e32 v40, v214
	v_mov_b32_e32 v41, v214
	v_mov_b32_e32 v42, v214
	v_mov_b32_e32 v43, v214
	v_mov_b32_e32 v44, v214
	v_mov_b32_e32 v45, v214
	v_mov_b32_e32 v46, v214
	v_mov_b32_e32 v47, v214
.Lat_ex2:
	s_add_i32 s10, s33, 96
	s_cmp_gt_i32 s10, s18
	s_cbranch_scc1 .Lat_ex3
	v_mov_b32_e32 v48, v214
	v_mov_b32_e32 v49, v214
	v_mov_b32_e32 v50, v214
	v_mov_b32_e32 v51, v214
	v_mov_b32_e32 v52, v214
	v_mov_b32_e32 v53, v214
	v_mov_b32_e32 v54, v214
	v_mov_b32_e32 v55, v214
	v_mov_b32_e32 v56, v214
	v_mov_b32_e32 v57, v214
	v_mov_b32_e32 v58, v214
	v_mov_b32_e32 v59, v214
	v_mov_b32_e32 v60, v214
	v_mov_b32_e32 v61, v214
	v_mov_b32_e32 v62, v214
	v_mov_b32_e32 v63, v214
.Lat_ex3:
	ds_read_b64_tr_b16 v[216:217], v252 offset:49152
	ds_read_b64_tr_b16 v[218:219], v252 offset:49664
	ds_read_b64_tr_b16 v[220:221], v252 offset:51200
	ds_read_b64_tr_b16 v[222:223], v252 offset:51712
	ds_read_b64_tr_b16 v[224:225], v252 offset:50176
	ds_read_b64_tr_b16 v[226:227], v252 offset:50688
	ds_read_b64_tr_b16 v[228:229], v252 offset:52224
	ds_read_b64_tr_b16 v[230:231], v252 offset:52736
	v_cndmask_b32_e64 v64, v64, v214, s[58:59]
	v_cndmask_b32_e64 v65, v214, v65, s[24:25]
	v_cndmask_b32_e64 v66, v214, v66, s[26:27]
	v_cndmask_b32_e64 v67, v214, v67, s[28:29]
	v_cndmask_b32_e64 v68, v68, v214, s[60:61]
	v_cndmask_b32_e64 v69, v214, v69, s[34:35]
	v_cndmask_b32_e64 v70, v214, v70, s[36:37]
	v_cndmask_b32_e64 v71, v214, v71, s[38:39]
	v_cndmask_b32_e64 v72, v72, v214, s[62:63]
	v_cndmask_b32_e64 v73, v214, v73, s[42:43]
	v_cndmask_b32_e64 v74, v214, v74, s[44:45]
	v_cndmask_b32_e64 v75, v214, v75, s[46:47]
	v_cndmask_b32_e64 v76, v76, v214, s[64:65]
	v_cndmask_b32_e64 v77, v214, v77, s[50:51]
	v_cndmask_b32_e64 v78, v214, v78, s[52:53]
	v_cndmask_b32_e64 v79, v214, v79, s[54:55]
	v_max3_f32 v254, v0, v1, v2
	v_max3_f32 v255, v3, v4, v5
	v_max3_f32 v254, v254, v6, v7
	v_max3_f32 v255, v255, v8, v9
	v_max3_f32 v254, v254, v10, v11
	v_max3_f32 v255, v255, v12, v13
	v_max3_f32 v254, v254, v14, v15
	v_max3_f32 v255, v255, v16, v17
	v_max3_f32 v254, v254, v18, v19
	v_max3_f32 v255, v255, v20, v21
	v_max3_f32 v254, v254, v22, v23
	v_max3_f32 v255, v255, v24, v25
	v_max3_f32 v254, v254, v26, v27
	v_max3_f32 v255, v255, v28, v29
	v_max3_f32 v254, v254, v30, v31
	v_max3_f32 v255, v255, v32, v33
	v_max3_f32 v254, v254, v34, v35
	v_max3_f32 v255, v255, v36, v37
	v_max3_f32 v254, v254, v38, v39
	v_max3_f32 v255, v255, v40, v41
	v_max3_f32 v254, v254, v42, v43
	v_max3_f32 v255, v255, v44, v45
	v_max3_f32 v254, v254, v46, v47
	v_max3_f32 v255, v255, v48, v49
	v_max3_f32 v254, v254, v50, v51
	v_max3_f32 v255, v255, v52, v53
	v_max3_f32 v254, v254, v54, v55
	v_max3_f32 v255, v255, v56, v57
	v_max3_f32 v254, v254, v58, v59
	v_max3_f32 v255, v255, v60, v61
	v_max3_f32 v254, v254, v62, v63
	v_max3_f32 v255, v255, v64, v65
	v_max3_f32 v254, v254, v66, v67
	v_max3_f32 v255, v255, v68, v69
	v_max3_f32 v254, v254, v70, v71
	v_max3_f32 v255, v255, v72, v73
	v_max3_f32 v254, v254, v74, v75
	v_max3_f32 v255, v255, v76, v77
	v_max3_f32 v254, v254, v78, v79
	v_max_f32_e32 v215, v254, v255
	v_mov_b32_e32 v163, v215
	s_nop 1
	v_permlane32_swap_b32_e32 v215, v163
	v_max_f32_e32 v215, v215, v163
	v_sub_f32_e32 v0, v0, v215
	v_sub_f32_e32 v1, v1, v215
	v_sub_f32_e32 v2, v2, v215
	v_sub_f32_e32 v3, v3, v215
	v_sub_f32_e32 v4, v4, v215
	v_sub_f32_e32 v5, v5, v215
	v_sub_f32_e32 v6, v6, v215
	v_sub_f32_e32 v7, v7, v215
	v_sub_f32_e32 v8, v8, v215
	v_sub_f32_e32 v9, v9, v215
	v_sub_f32_e32 v10, v10, v215
	v_sub_f32_e32 v11, v11, v215
	v_sub_f32_e32 v12, v12, v215
	v_sub_f32_e32 v13, v13, v215
	v_sub_f32_e32 v14, v14, v215
	v_sub_f32_e32 v15, v15, v215
	v_exp_f32_e32 v0, v0
	v_exp_f32_e32 v1, v1
	v_exp_f32_e32 v2, v2
	v_exp_f32_e32 v3, v3
	v_exp_f32_e32 v4, v4
	v_exp_f32_e32 v5, v5
	v_exp_f32_e32 v6, v6
	v_exp_f32_e32 v7, v7
	v_exp_f32_e32 v8, v8
	v_exp_f32_e32 v9, v9
	v_exp_f32_e32 v10, v10
	v_exp_f32_e32 v11, v11
	v_exp_f32_e32 v12, v12
	v_exp_f32_e32 v13, v13
	v_exp_f32_e32 v14, v14
	v_exp_f32_e32 v15, v15
	v_add_f32_e32 v249, v0, v2
	v_add_f32_e32 v250, v1, v3
	v_add_f32_e32 v249, v249, v4
	v_add_f32_e32 v250, v250, v5
	v_add_f32_e32 v249, v249, v6
	v_add_f32_e32 v250, v250, v7
	v_add_f32_e32 v249, v249, v8
	v_add_f32_e32 v250, v250, v9
	v_add_f32_e32 v249, v249, v10
	v_add_f32_e32 v250, v250, v11
	v_add_f32_e32 v249, v249, v12
	v_add_f32_e32 v250, v250, v13
	v_add_f32_e32 v249, v249, v14
	v_add_f32_e32 v250, v250, v15
	v_cvt_pk_bf16_f32 v0, v0, v1
	v_cvt_pk_bf16_f32 v1, v2, v3
	v_cvt_pk_bf16_f32 v2, v4, v5
	v_cvt_pk_bf16_f32 v3, v6, v7
	v_cvt_pk_bf16_f32 v4, v8, v9
	v_cvt_pk_bf16_f32 v5, v10, v11
	v_cvt_pk_bf16_f32 v6, v12, v13
	v_cvt_pk_bf16_f32 v7, v14, v15
	v_sub_f32_e32 v16, v16, v215
	v_sub_f32_e32 v17, v17, v215
	v_sub_f32_e32 v18, v18, v215
	v_sub_f32_e32 v19, v19, v215
	s_waitcnt lgkmcnt(6)
	v_mfma_f32_32x32x16_bf16 v[80:95], v[216:219], v[0:3], 0
	v_sub_f32_e32 v20, v20, v215
	v_sub_f32_e32 v21, v21, v215
	v_sub_f32_e32 v22, v22, v215
	v_sub_f32_e32 v23, v23, v215
	v_sub_f32_e32 v24, v24, v215
	v_sub_f32_e32 v25, v25, v215
	v_sub_f32_e32 v26, v26, v215
	v_sub_f32_e32 v27, v27, v215
	v_sub_f32_e32 v28, v28, v215
	v_sub_f32_e32 v29, v29, v215
	v_sub_f32_e32 v30, v30, v215
	v_sub_f32_e32 v31, v31, v215
	v_exp_f32_e32 v16, v16
	v_exp_f32_e32 v17, v17
	s_waitcnt lgkmcnt(4)
	v_mfma_f32_32x32x16_bf16 v[232:247], v[220:223], v[0:3], 0
	ds_read_b64_tr_b16 v[216:217], v252 offset:53248
	ds_read_b64_tr_b16 v[218:219], v252 offset:53760
	ds_read_b64_tr_b16 v[220:221], v252 offset:55296
	ds_read_b64_tr_b16 v[222:223], v252 offset:55808
	v_exp_f32_e32 v18, v18
	v_exp_f32_e32 v19, v19
	v_exp_f32_e32 v20, v20
	v_exp_f32_e32 v21, v21
	v_exp_f32_e32 v22, v22
	v_exp_f32_e32 v23, v23
	v_exp_f32_e32 v24, v24
	v_exp_f32_e32 v25, v25
	v_exp_f32_e32 v26, v26
	v_exp_f32_e32 v27, v27
	v_exp_f32_e32 v28, v28
	v_exp_f32_e32 v29, v29
	v_exp_f32_e32 v30, v30
	v_exp_f32_e32 v31, v31
	s_waitcnt lgkmcnt(6)
	v_mfma_f32_32x32x16_bf16 v[80:95], v[224:227], v[4:7], v[80:95]
	v_add_f32_e32 v249, v249, v16
	v_add_f32_e32 v250, v250, v17
	v_add_f32_e32 v249, v249, v18
	v_add_f32_e32 v250, v250, v19
	v_add_f32_e32 v249, v249, v20
	v_add_f32_e32 v250, v250, v21
	v_add_f32_e32 v249, v249, v22
	v_add_f32_e32 v250, v250, v23
	v_add_f32_e32 v249, v249, v24
	v_add_f32_e32 v250, v250, v25
	v_add_f32_e32 v249, v249, v26
	v_add_f32_e32 v250, v250, v27
	v_add_f32_e32 v249, v249, v28
	v_add_f32_e32 v250, v250, v29
	s_waitcnt lgkmcnt(4)
	v_mfma_f32_32x32x16_bf16 v[232:247], v[228:231], v[4:7], v[232:247]
	ds_read_b64_tr_b16 v[224:225], v252 offset:54272
	ds_read_b64_tr_b16 v[226:227], v252 offset:54784
	ds_read_b64_tr_b16 v[228:229], v252 offset:56320
	ds_read_b64_tr_b16 v[230:231], v252 offset:56832
	v_add_f32_e32 v249, v249, v30
	v_add_f32_e32 v250, v250, v31
	v_cvt_pk_bf16_f32 v16, v16, v17
	v_cvt_pk_bf16_f32 v17, v18, v19
	v_cvt_pk_bf16_f32 v18, v20, v21
	v_cvt_pk_bf16_f32 v19, v22, v23
	v_cvt_pk_bf16_f32 v20, v24, v25
	v_cvt_pk_bf16_f32 v21, v26, v27
	v_cvt_pk_bf16_f32 v22, v28, v29
	v_cvt_pk_bf16_f32 v23, v30, v31
	v_sub_f32_e32 v32, v32, v215
	v_sub_f32_e32 v33, v33, v215
	v_sub_f32_e32 v34, v34, v215
	v_sub_f32_e32 v35, v35, v215
	s_waitcnt lgkmcnt(6)
	v_mfma_f32_32x32x16_bf16 v[80:95], v[216:219], v[16:19], v[80:95]
	v_sub_f32_e32 v36, v36, v215
	v_sub_f32_e32 v37, v37, v215
	v_sub_f32_e32 v38, v38, v215
	v_sub_f32_e32 v39, v39, v215
	v_sub_f32_e32 v40, v40, v215
	v_sub_f32_e32 v41, v41, v215
	v_sub_f32_e32 v42, v42, v215
	v_sub_f32_e32 v43, v43, v215
	v_sub_f32_e32 v44, v44, v215
	v_sub_f32_e32 v45, v45, v215
	v_sub_f32_e32 v46, v46, v215
	v_sub_f32_e32 v47, v47, v215
	v_exp_f32_e32 v32, v32
	v_exp_f32_e32 v33, v33
	s_waitcnt lgkmcnt(4)
	v_mfma_f32_32x32x16_bf16 v[232:247], v[220:223], v[16:19], v[232:247]
	ds_read_b64_tr_b16 v[216:217], v252 offset:57344
	ds_read_b64_tr_b16 v[218:219], v252 offset:57856
	ds_read_b64_tr_b16 v[220:221], v252 offset:59392
	ds_read_b64_tr_b16 v[222:223], v252 offset:59904
	v_exp_f32_e32 v34, v34
	v_exp_f32_e32 v35, v35
	v_exp_f32_e32 v36, v36
	v_exp_f32_e32 v37, v37
	v_exp_f32_e32 v38, v38
	v_exp_f32_e32 v39, v39
	v_exp_f32_e32 v40, v40
	v_exp_f32_e32 v41, v41
	v_exp_f32_e32 v42, v42
	v_exp_f32_e32 v43, v43
	v_exp_f32_e32 v44, v44
	v_exp_f32_e32 v45, v45
	v_exp_f32_e32 v46, v46
	v_exp_f32_e32 v47, v47
	s_waitcnt lgkmcnt(6)
	v_mfma_f32_32x32x16_bf16 v[80:95], v[224:227], v[20:23], v[80:95]
	v_add_f32_e32 v249, v249, v32
	v_add_f32_e32 v250, v250, v33
	v_add_f32_e32 v249, v249, v34
	v_add_f32_e32 v250, v250, v35
	v_add_f32_e32 v249, v249, v36
	v_add_f32_e32 v250, v250, v37
	v_add_f32_e32 v249, v249, v38
	v_add_f32_e32 v250, v250, v39
	v_add_f32_e32 v249, v249, v40
	v_add_f32_e32 v250, v250, v41
	v_add_f32_e32 v249, v249, v42
	v_add_f32_e32 v250, v250, v43
	v_add_f32_e32 v249, v249, v44
	v_add_f32_e32 v250, v250, v45
	s_waitcnt lgkmcnt(4)
	v_mfma_f32_32x32x16_bf16 v[232:247], v[228:231], v[20:23], v[232:247]
	ds_read_b64_tr_b16 v[224:225], v252 offset:58368
	ds_read_b64_tr_b16 v[226:227], v252 offset:58880
	ds_read_b64_tr_b16 v[228:229], v252 offset:60416
	ds_read_b64_tr_b16 v[230:231], v252 offset:60928
	v_add_f32_e32 v249, v249, v46
	v_add_f32_e32 v250, v250, v47
	v_cvt_pk_bf16_f32 v32, v32, v33
	v_cvt_pk_bf16_f32 v33, v34, v35
	v_cvt_pk_bf16_f32 v34, v36, v37
	v_cvt_pk_bf16_f32 v35, v38, v39
	v_cvt_pk_bf16_f32 v36, v40, v41
	v_cvt_pk_bf16_f32 v37, v42, v43
	v_cvt_pk_bf16_f32 v38, v44, v45
	v_cvt_pk_bf16_f32 v39, v46, v47
	v_sub_f32_e32 v48, v48, v215
	v_sub_f32_e32 v49, v49, v215
	v_sub_f32_e32 v50, v50, v215
	v_sub_f32_e32 v51, v51, v215
	s_waitcnt lgkmcnt(6)
	v_mfma_f32_32x32x16_bf16 v[80:95], v[216:219], v[32:35], v[80:95]
	v_sub_f32_e32 v52, v52, v215
	v_sub_f32_e32 v53, v53, v215
	v_sub_f32_e32 v54, v54, v215
	v_sub_f32_e32 v55, v55, v215
	v_sub_f32_e32 v56, v56, v215
	v_sub_f32_e32 v57, v57, v215
	v_sub_f32_e32 v58, v58, v215
	v_sub_f32_e32 v59, v59, v215
	v_sub_f32_e32 v60, v60, v215
	v_sub_f32_e32 v61, v61, v215
	v_sub_f32_e32 v62, v62, v215
	v_sub_f32_e32 v63, v63, v215
	v_exp_f32_e32 v48, v48
	v_exp_f32_e32 v49, v49
	s_waitcnt lgkmcnt(4)
	v_mfma_f32_32x32x16_bf16 v[232:247], v[220:223], v[32:35], v[232:247]
	ds_read_b64_tr_b16 v[216:217], v253 offset:49152
	ds_read_b64_tr_b16 v[218:219], v253 offset:49664
	ds_read_b64_tr_b16 v[220:221], v253 offset:51200
	ds_read_b64_tr_b16 v[222:223], v253 offset:51712
	v_exp_f32_e32 v50, v50
	v_exp_f32_e32 v51, v51
	v_exp_f32_e32 v52, v52
	v_exp_f32_e32 v53, v53
	v_exp_f32_e32 v54, v54
	v_exp_f32_e32 v55, v55
	v_exp_f32_e32 v56, v56
	v_exp_f32_e32 v57, v57
	v_exp_f32_e32 v58, v58
	v_exp_f32_e32 v59, v59
	v_exp_f32_e32 v60, v60
	v_exp_f32_e32 v61, v61
	v_exp_f32_e32 v62, v62
	v_exp_f32_e32 v63, v63
	s_waitcnt lgkmcnt(6)
	v_mfma_f32_32x32x16_bf16 v[80:95], v[224:227], v[36:39], v[80:95]
	v_add_f32_e32 v249, v249, v48
	v_add_f32_e32 v250, v250, v49
	v_add_f32_e32 v249, v249, v50
	v_add_f32_e32 v250, v250, v51
	v_add_f32_e32 v249, v249, v52
	v_add_f32_e32 v250, v250, v53
	v_add_f32_e32 v249, v249, v54
	v_add_f32_e32 v250, v250, v55
	v_add_f32_e32 v249, v249, v56
	v_add_f32_e32 v250, v250, v57
	v_add_f32_e32 v249, v249, v58
	v_add_f32_e32 v250, v250, v59
	v_add_f32_e32 v249, v249, v60
	v_add_f32_e32 v250, v250, v61
	s_waitcnt lgkmcnt(4)
	v_mfma_f32_32x32x16_bf16 v[232:247], v[228:231], v[36:39], v[232:247]
	ds_read_b64_tr_b16 v[224:225], v253 offset:50176
	ds_read_b64_tr_b16 v[226:227], v253 offset:50688
	ds_read_b64_tr_b16 v[228:229], v253 offset:52224
	ds_read_b64_tr_b16 v[230:231], v253 offset:52736
	v_add_f32_e32 v249, v249, v62
	v_add_f32_e32 v250, v250, v63
	v_cvt_pk_bf16_f32 v48, v48, v49
	v_cvt_pk_bf16_f32 v49, v50, v51
	v_cvt_pk_bf16_f32 v50, v52, v53
	v_cvt_pk_bf16_f32 v51, v54, v55
	v_cvt_pk_bf16_f32 v52, v56, v57
	v_cvt_pk_bf16_f32 v53, v58, v59
	v_cvt_pk_bf16_f32 v54, v60, v61
	v_cvt_pk_bf16_f32 v55, v62, v63
	v_sub_f32_e32 v64, v64, v215
	v_sub_f32_e32 v65, v65, v215
	v_sub_f32_e32 v66, v66, v215
	v_sub_f32_e32 v67, v67, v215
	s_waitcnt lgkmcnt(6)
	v_mfma_f32_32x32x16_bf16 v[80:95], v[216:219], v[48:51], v[80:95]
	v_sub_f32_e32 v68, v68, v215
	v_sub_f32_e32 v69, v69, v215
	v_sub_f32_e32 v70, v70, v215
	v_sub_f32_e32 v71, v71, v215
	v_sub_f32_e32 v72, v72, v215
	v_sub_f32_e32 v73, v73, v215
	v_sub_f32_e32 v74, v74, v215
	v_sub_f32_e32 v75, v75, v215
	v_sub_f32_e32 v76, v76, v215
	v_sub_f32_e32 v77, v77, v215
	v_sub_f32_e32 v78, v78, v215
	v_sub_f32_e32 v79, v79, v215
	v_exp_f32_e32 v64, v64
	v_exp_f32_e32 v65, v65
	s_waitcnt lgkmcnt(4)
	v_mfma_f32_32x32x16_bf16 v[232:247], v[220:223], v[48:51], v[232:247]
	ds_read_b64_tr_b16 v[216:217], v253 offset:53248
	ds_read_b64_tr_b16 v[218:219], v253 offset:53760
	ds_read_b64_tr_b16 v[220:221], v253 offset:55296
	ds_read_b64_tr_b16 v[222:223], v253 offset:55808
	v_exp_f32_e32 v66, v66
	v_exp_f32_e32 v67, v67
	v_exp_f32_e32 v68, v68
	v_exp_f32_e32 v69, v69
	v_exp_f32_e32 v70, v70
	v_exp_f32_e32 v71, v71
	v_exp_f32_e32 v72, v72
	v_exp_f32_e32 v73, v73
	v_exp_f32_e32 v74, v74
	v_exp_f32_e32 v75, v75
	v_exp_f32_e32 v76, v76
	v_exp_f32_e32 v77, v77
	v_exp_f32_e32 v78, v78
	v_exp_f32_e32 v79, v79
	s_waitcnt lgkmcnt(6)
	v_mfma_f32_32x32x16_bf16 v[80:95], v[224:227], v[52:55], v[80:95]
	v_add_f32_e32 v249, v249, v64
	v_add_f32_e32 v250, v250, v65
	v_add_f32_e32 v249, v249, v66
	v_add_f32_e32 v250, v250, v67
	v_add_f32_e32 v249, v249, v68
	v_add_f32_e32 v250, v250, v69
	v_add_f32_e32 v249, v249, v70
	v_add_f32_e32 v250, v250, v71
	v_add_f32_e32 v249, v249, v72
	v_add_f32_e32 v250, v250, v73
	v_add_f32_e32 v249, v249, v74
	v_add_f32_e32 v250, v250, v75
	v_add_f32_e32 v249, v249, v76
	v_add_f32_e32 v250, v250, v77
	s_waitcnt lgkmcnt(4)
	v_mfma_f32_32x32x16_bf16 v[232:247], v[228:231], v[52:55], v[232:247]
	ds_read_b64_tr_b16 v[224:225], v253 offset:54272
	ds_read_b64_tr_b16 v[226:227], v253 offset:54784
	ds_read_b64_tr_b16 v[228:229], v253 offset:56320
	ds_read_b64_tr_b16 v[230:231], v253 offset:56832
	v_add_f32_e32 v249, v249, v78
	v_add_f32_e32 v250, v250, v79
	v_cvt_pk_bf16_f32 v64, v64, v65
	v_cvt_pk_bf16_f32 v65, v66, v67
	v_cvt_pk_bf16_f32 v66, v68, v69
	v_cvt_pk_bf16_f32 v67, v70, v71
	v_cvt_pk_bf16_f32 v68, v72, v73
	v_cvt_pk_bf16_f32 v69, v74, v75
	v_cvt_pk_bf16_f32 v70, v76, v77
	v_cvt_pk_bf16_f32 v71, v78, v79
	s_waitcnt lgkmcnt(6)
	v_mfma_f32_32x32x16_bf16 v[80:95], v[216:219], v[64:67], v[80:95]
	v_add_f32_e32 v249, v249, v250
	v_mov_b32_e32 v163, v249
	s_sub_i32 s8, 4, s96
	s_lshr_b32 s8, s7, s8
	v_permlane32_swap_b32_e32 v249, v163
	s_waitcnt lgkmcnt(4)
	v_mfma_f32_32x32x16_bf16 v[232:247], v[220:223], v[64:67], v[232:247]
	v_add_f32_e32 v249, v249, v163
	s_ashr_i32 s7, s6, 31
	s_lshl_b64 s[6:7], s[6:7], 12
	s_or_b32 s6, s6, s8
	v_rcp_f32_e32 v250, v249
	v_log_f32_e32 v163, v249
	s_waitcnt lgkmcnt(2)
	v_mfma_f32_32x32x16_bf16 v[80:95], v[224:227], v[68:71], v[80:95]
	v_readlane_b32 s12, v248, 22
	v_readlane_b32 s13, v248, 23
	v_fma_f32 v251, -v249, v250, 2.0
	v_add_f32_e32 v163, v215, v163
	v_mul_f32_e32 v250, v250, v251
	s_waitcnt lgkmcnt(0)
	v_mfma_f32_32x32x16_bf16 v[232:247], v[228:231], v[68:71], v[232:247]
	s_add_i32 s10, s1, s33
	s_ashr_i32 s1, s0, 31
	s_lshl_b64 s[8:9], s[0:1], 25
	s_add_u32 s8, s74, s8
	s_addc_u32 s9, s75, s9
	s_cmp_eq_u32 s0, 2
	s_cselect_b32 s8, s12, s8
	s_cselect_b32 s9, s13, s9
	s_add_u32 s8, s8, s94
	s_addc_u32 s9, s9, 0
	v_lshl_add_u64 v[24:25], s[8:9], 0, v[160:161]
	v_or_b32_e32 v16, s10, v164
	v_mov_b32_e32 v17, v161
	v_lshlrev_b64 v[16:17], s96, v[16:17]
	v_lshl_add_u64 v[16:17], v[16:17], 0, s[6:7]
	v_lshlrev_b64 v[16:17], 10, v[16:17]
	v_lshl_add_u64 v[16:17], v[24:25], 0, v[16:17]
	v_or_b32_e32 v18, s10, v187
	v_mov_b32_e32 v19, v161
	v_lshlrev_b64 v[18:19], s96, v[18:19]
	v_lshl_add_u64 v[18:19], v[18:19], 0, s[6:7]
	v_lshlrev_b64 v[18:19], 10, v[18:19]
	v_lshl_add_u64 v[18:19], v[24:25], 0, v[18:19]
	v_or_b32_e32 v20, s10, v188
	v_mov_b32_e32 v21, v161
	v_lshlrev_b64 v[20:21], s96, v[20:21]
	v_lshl_add_u64 v[20:21], v[20:21], 0, s[6:7]
	v_lshlrev_b64 v[20:21], 10, v[20:21]
	v_lshl_add_u64 v[20:21], v[24:25], 0, v[20:21]
	v_or_b32_e32 v22, s10, v189
	v_mov_b32_e32 v23, v161
	v_lshlrev_b64 v[22:23], s96, v[22:23]
	v_lshl_add_u64 v[22:23], v[22:23], 0, s[6:7]
	v_lshlrev_b64 v[22:23], 10, v[22:23]
	v_lshl_add_u64 v[22:23], v[24:25], 0, v[22:23]
	v_add_u32_e32 v26, v171, v186
	s_nop 3
	v_mul_f32_e32 v80, v80, v250
	v_mul_f32_e32 v81, v81, v250
	v_mul_f32_e32 v82, v82, v250
	v_mul_f32_e32 v83, v83, v250
	v_cvt_pk_bf16_f32 v80, v80, v81
	v_cvt_pk_bf16_f32 v81, v82, v83
	v_mul_f32_e32 v232, v232, v250
	v_mul_f32_e32 v233, v233, v250
	v_mul_f32_e32 v234, v234, v250
	v_mul_f32_e32 v235, v235, v250
	v_cvt_pk_bf16_f32 v232, v232, v233
	v_cvt_pk_bf16_f32 v233, v234, v235
	ds_write_b64 v26, v[80:81]
	ds_write_b64 v204, v[232:233]
	v_mul_f32_e32 v84, v84, v250
	v_mul_f32_e32 v85, v85, v250
	v_mul_f32_e32 v86, v86, v250
	v_mul_f32_e32 v87, v87, v250
	v_cvt_pk_bf16_f32 v84, v84, v85
	v_cvt_pk_bf16_f32 v85, v86, v87
	v_mul_f32_e32 v236, v236, v250
	v_mul_f32_e32 v237, v237, v250
	v_mul_f32_e32 v238, v238, v250
	v_mul_f32_e32 v239, v239, v250
	v_cvt_pk_bf16_f32 v236, v236, v237
	v_cvt_pk_bf16_f32 v237, v238, v239
	ds_write_b64 v205, v[84:85]
	ds_write_b64 v206, v[236:237]
	v_mul_f32_e32 v88, v88, v250
	v_mul_f32_e32 v89, v89, v250
	v_mul_f32_e32 v90, v90, v250
	v_mul_f32_e32 v91, v91, v250
	v_cvt_pk_bf16_f32 v88, v88, v89
	v_cvt_pk_bf16_f32 v89, v90, v91
	v_mul_f32_e32 v240, v240, v250
	v_mul_f32_e32 v241, v241, v250
	v_mul_f32_e32 v242, v242, v250
	v_mul_f32_e32 v243, v243, v250
	v_cvt_pk_bf16_f32 v240, v240, v241
	v_cvt_pk_bf16_f32 v241, v242, v243
	ds_write_b64 v207, v[88:89]
	ds_write_b64 v208, v[240:241]
	v_mul_f32_e32 v92, v92, v250
	v_mul_f32_e32 v93, v93, v250
	v_mul_f32_e32 v94, v94, v250
	v_mul_f32_e32 v95, v95, v250
	v_cvt_pk_bf16_f32 v92, v92, v93
	v_cvt_pk_bf16_f32 v93, v94, v95
	v_mul_f32_e32 v244, v244, v250
	v_mul_f32_e32 v245, v245, v250
	v_mul_f32_e32 v246, v246, v250
	v_mul_f32_e32 v247, v247, v250
	v_cvt_pk_bf16_f32 v244, v244, v245
	v_cvt_pk_bf16_f32 v245, v246, v247
	ds_write_b64 v209, v[92:93]
	ds_write_b64 v210, v[244:245]
	v_add_u32_e32 v27, v172, v167
	ds_read_b128 v[0:3], v27
	ds_read_b128 v[4:7], v211
	ds_read_b128 v[8:11], v212
	ds_read_b128 v[12:15], v213
	s_waitcnt lgkmcnt(3)
	global_store_dwordx4 v[16:17], v[0:3], off
	s_waitcnt lgkmcnt(2)
	global_store_dwordx4 v[18:19], v[4:7], off
	s_waitcnt lgkmcnt(1)
	global_store_dwordx4 v[20:21], v[8:11], off
	s_waitcnt lgkmcnt(0)
	global_store_dwordx4 v[22:23], v[12:15], off
	s_mov_b64 s[8:9], exec
	v_readlane_b32 s12, v248, 37
	v_readlane_b32 s13, v248, 38
	s_and_b64 s[12:13], s[8:9], s[12:13]
	s_mov_b64 exec, s[12:13]
	s_cbranch_execz .LBB0_233
	v_or_b32_e32 v0, s10, v166
	v_mov_b32_e32 v1, v161
	v_lshlrev_b64 v[0:1], s96, v[0:1]
	v_lshl_add_u64 v[0:1], v[0:1], 0, s[6:7]
	s_lshl_b64 s[0:1], s[0:1], 20
	v_readlane_b32 s6, v248, 24
	v_readlane_b32 s7, v248, 25
	v_lshlrev_b64 v[0:1], 5, v[0:1]
	s_nop 0
	s_add_u32 s0, s6, s0
	s_addc_u32 s1, s7, s1
	v_lshl_add_u64 v[0:1], s[0:1], 0, v[0:1]
	s_lshl_b32 s0, s21, 2
	s_mov_b32 s1, s68
	v_lshl_add_u64 v[0:1], v[0:1], 0, s[0:1]
	global_store_dword v[0:1], v163, off
	s_branch .LBB0_233

.LBB0_348:
	s_mov_b32 s0, 0
	s_mov_b32 s1, 0
.Lmg_t:
	s_add_i32 s0, s0, s78
	s_add_i32 s1, s1, 1
	s_cmp_lt_i32 s0, 0x8000
	s_cbranch_scc1 .Lmg_t
	s_mul_i32 s2, s76, s1
	s_add_i32 s3, s2, s1
	s_min_i32 s3, s3, 0x8000
	s_cmp_ge_i32 s2, s3
	s_cbranch_scc1 .LBB0_363
	s_mov_b32 s30, s2
	s_mov_b32 s9, 0xffff0000
	s_mov_b32 s31, 0x3b000000
	v_mov_b32_e32 v63, 0x358637bd
	v_and_b32_e32 v2, 63, v200
	v_lshlrev_b32_e32 v0, 4, v2
	v_lshlrev_b32_e32 v3, 5, v2
	v_lshrrev_b32_e32 v2, 3, v2
	v_lshlrev_b32_e32 v1, 2, v2
	s_add_u32 s4, s88, 0x5200000
	s_addc_u32 s5, s89, 0
	s_lshr_b32 s1, s2, 27
	s_lshl_b32 s0, s2, 5
	s_add_u32 s4, s4, s0
	s_addc_u32 s5, s5, s1
	s_add_u32 s10, s88, 0x5300000
	s_addc_u32 s11, s89, 0
	s_lshr_b32 s1, s2, 27
	s_lshl_b32 s0, s2, 5
	s_add_u32 s10, s10, s0
	s_addc_u32 s11, s11, s1
	s_add_u32 s14, s88, 0x5400000
	s_addc_u32 s15, s89, 0
	s_lshr_b32 s1, s2, 27
	s_lshl_b32 s0, s2, 5
	s_add_u32 s14, s14, s0
	s_addc_u32 s15, s15, s1
	s_add_u32 s18, s88, 0x6000000
	s_addc_u32 s19, s89, 0
	s_lshr_b32 s1, s2, 22
	s_lshl_b32 s0, s2, 10
	s_add_u32 s18, s18, s0
	s_addc_u32 s19, s19, s1
	s_add_u32 s20, s88, 0x8000000
	s_addc_u32 s21, s89, 0
	s_lshr_b32 s1, s2, 22
	s_lshl_b32 s0, s2, 10
	s_add_u32 s20, s20, s0
	s_addc_u32 s21, s21, s1
	s_add_u32 s22, s88, 0x1a600000
	s_addc_u32 s23, s89, 0
	s_lshr_b32 s1, s2, 22
	s_lshl_b32 s0, s2, 10
	s_add_u32 s22, s22, s0
	s_addc_u32 s23, s23, s1
	s_add_u32 s26, s88, 0xa000000
	s_addc_u32 s27, s89, 0
	s_mul_hi_u32 s1, s2, 3072
	s_mul_i32 s0, s2, 3072
	s_add_u32 s26, s26, s0
	s_addc_u32 s27, s27, s1
	s_add_u32 s28, s88, 0x16600000
	s_addc_u32 s29, s89, 0
	s_lshr_b32 s1, s2, 21
	s_lshl_b32 s0, s2, 11
	s_add_u32 s28, s28, s0
	s_addc_u32 s29, s29, s1
	v_readlane_b32 s48, v248, 10
	v_readlane_b32 s49, v248, 11
	v_readlane_b32 s50, v248, 12
	v_readlane_b32 s51, v248, 13
	v_readlane_b32 s52, v248, 14
	v_readlane_b32 s53, v248, 15
	s_nop 3
	s_add_u32 s54, s48, 0x1000
	s_addc_u32 s55, s49, 0
	global_load_dwordx4 v[4:7], v3, s[48:49]
	global_load_dwordx4 v[8:11], v3, s[48:49] offset:16
	global_load_dwordx4 v[12:15], v3, s[48:49] offset:2048
	global_load_dwordx4 v[16:19], v3, s[48:49] offset:2064
	global_load_dwordx4 v[20:23], v3, s[54:55]
	global_load_dwordx4 v[24:27], v3, s[54:55] offset:16
	global_load_dwordx4 v[28:31], v3, s[50:51]
	global_load_dwordx4 v[32:35], v3, s[50:51] offset:16
	global_load_dwordx4 v[36:39], v3, s[52:53]
	global_load_dwordx4 v[40:43], v3, s[52:53] offset:16
	s_and_b32 s17, s2, 0xfff
	s_cmp_ge_u32 s17, 1
	s_cselect_b32 s0, 0xc00, 0
	s_sub_u32 s34, s26, s0
	s_subb_u32 s35, s27, 0
	s_cmp_ge_u32 s17, 2
	s_cselect_b32 s0, 0x1800, 0
	s_sub_u32 s36, s26, s0
	s_subb_u32 s37, s27, 0
	global_load_dwordx4 v[156:159], v0, s[34:35] offset:1024
	global_load_dwordx4 v[160:163], v0, s[34:35] offset:2048
	global_load_dwordx4 v[164:167], v0, s[36:37] offset:1024
	global_load_dwordx4 v[168:171], v0, s[36:37] offset:2048
	global_load_dword v60, v1, s[4:5] nt
	global_load_dword v61, v1, s[10:11] nt
	global_load_dword v62, v1, s[14:15] nt
	global_load_dwordx4 v[64:67], v0, s[18:19] nt
	global_load_dwordx4 v[68:71], v0, s[20:21] nt
	global_load_dwordx4 v[72:75], v0, s[22:23] nt
	global_load_dwordx4 v[76:79], v0, s[26:27]
	global_load_dwordx4 v[80:83], v0, s[26:27] offset:1024
	global_load_dwordx4 v[84:87], v0, s[26:27] offset:2048
	s_add_u32 s4, s4, 32
	s_addc_u32 s5, s5, 0
	s_add_u32 s10, s10, 32
	s_addc_u32 s11, s11, 0
	s_add_u32 s14, s14, 32
	s_addc_u32 s15, s15, 0
	s_add_u32 s18, s18, 0x400
	s_addc_u32 s19, s19, 0
	s_add_u32 s20, s20, 0x400
	s_addc_u32 s21, s21, 0
	s_add_u32 s22, s22, 0x400
	s_addc_u32 s23, s23, 0
	s_add_u32 s26, s26, 0xc00
	s_addc_u32 s27, s27, 0
	s_add_i32 s30, s30, 1
	s_cmp_lt_i32 s30, s3
	s_cbranch_scc0 .Lmg_h1
	global_load_dword v88, v1, s[4:5] nt
	global_load_dword v89, v1, s[10:11] nt
	global_load_dword v90, v1, s[14:15] nt
	global_load_dwordx4 v[92:95], v0, s[18:19] nt
	global_load_dwordx4 v[96:99], v0, s[20:21] nt
	global_load_dwordx4 v[100:103], v0, s[22:23] nt
	global_load_dwordx4 v[104:107], v0, s[26:27]
	global_load_dwordx4 v[108:111], v0, s[26:27] offset:1024
	global_load_dwordx4 v[112:115], v0, s[26:27] offset:2048
	s_add_u32 s4, s4, 32
	s_addc_u32 s5, s5, 0
	s_add_u32 s10, s10, 32
	s_addc_u32 s11, s11, 0
	s_add_u32 s14, s14, 32
	s_addc_u32 s15, s15, 0
	s_add_u32 s18, s18, 0x400
	s_addc_u32 s19, s19, 0
	s_add_u32 s20, s20, 0x400
	s_addc_u32 s21, s21, 0
	s_add_u32 s22, s22, 0x400
	s_addc_u32 s23, s23, 0
	s_add_u32 s26, s26, 0xc00
	s_addc_u32 s27, s27, 0
	s_add_i32 s30, s30, 1
	s_cmp_lt_i32 s30, s3
	s_cbranch_scc0 .Lmg_h1
	global_load_dword v116, v1, s[4:5] nt
	global_load_dword v117, v1, s[10:11] nt
	global_load_dword v118, v1, s[14:15] nt
	global_load_dwordx4 v[120:123], v0, s[18:19] nt
	global_load_dwordx4 v[124:127], v0, s[20:21] nt
	global_load_dwordx4 v[128:131], v0, s[22:23] nt
	global_load_dwordx4 v[132:135], v0, s[26:27]
	global_load_dwordx4 v[136:139], v0, s[26:27] offset:1024
	global_load_dwordx4 v[144:147], v0, s[26:27] offset:2048
	s_add_u32 s4, s4, 32
	s_addc_u32 s5, s5, 0
	s_add_u32 s10, s10, 32
	s_addc_u32 s11, s11, 0
	s_add_u32 s14, s14, 32
	s_addc_u32 s15, s15, 0
	s_add_u32 s18, s18, 0x400
	s_addc_u32 s19, s19, 0
	s_add_u32 s20, s20, 0x400
	s_addc_u32 s21, s21, 0
	s_add_u32 s22, s22, 0x400
	s_addc_u32 s23, s23, 0
	s_add_u32 s26, s26, 0xc00
	s_addc_u32 s27, s27, 0
	s_add_i32 s30, s30, 1
	s_waitcnt vmcnt(27)
	s_branch .Lmg_h2

.Lmg_h2:
	v_lshlrev_b32_e32 v172, 16, v156
	v_and_b32_e32 v173, s9, v156
	v_lshlrev_b32_e32 v174, 16, v160
	v_and_b32_e32 v175, s9, v160
	v_mul_f32_e32 v44, v172, v174
	v_mul_f32_e32 v45, v173, v175
	v_lshlrev_b32_e32 v172, 16, v164
	v_and_b32_e32 v173, s9, v164
	v_lshlrev_b32_e32 v174, 16, v168
	v_and_b32_e32 v175, s9, v168
	v_mul_f32_e32 v52, v172, v174
	v_mul_f32_e32 v53, v173, v175
	v_lshlrev_b32_e32 v172, 16, v157
	v_and_b32_e32 v173, s9, v157
	v_lshlrev_b32_e32 v174, 16, v161
	v_and_b32_e32 v175, s9, v161
	v_mul_f32_e32 v46, v172, v174
	v_mul_f32_e32 v47, v173, v175
	v_lshlrev_b32_e32 v172, 16, v165
	v_and_b32_e32 v173, s9, v165
	v_lshlrev_b32_e32 v174, 16, v169
	v_and_b32_e32 v175, s9, v169
	v_mul_f32_e32 v54, v172, v174
	v_mul_f32_e32 v55, v173, v175
	v_lshlrev_b32_e32 v172, 16, v158
	v_and_b32_e32 v173, s9, v158
	v_lshlrev_b32_e32 v174, 16, v162
	v_and_b32_e32 v175, s9, v162
	v_mul_f32_e32 v48, v172, v174
	v_mul_f32_e32 v49, v173, v175
	v_lshlrev_b32_e32 v172, 16, v166
	v_and_b32_e32 v173, s9, v166
	v_lshlrev_b32_e32 v174, 16, v170
	v_and_b32_e32 v175, s9, v170
	v_mul_f32_e32 v56, v172, v174
	v_mul_f32_e32 v57, v173, v175
	v_lshlrev_b32_e32 v172, 16, v159
	v_and_b32_e32 v173, s9, v159
	v_lshlrev_b32_e32 v174, 16, v163
	v_and_b32_e32 v175, s9, v163
	v_mul_f32_e32 v50, v172, v174
	v_mul_f32_e32 v51, v173, v175
	v_lshlrev_b32_e32 v172, 16, v167
	v_and_b32_e32 v173, s9, v167
	v_lshlrev_b32_e32 v174, 16, v171
	v_and_b32_e32 v175, s9, v171
	v_mul_f32_e32 v58, v172, v174
	v_mul_f32_e32 v59, v173, v175
	s_cmp_ge_u32 s17, 2
	s_cbranch_scc1 .Lmg_h3
	v_mov_b32_e32 v52, 0
	v_mov_b32_e32 v53, 0
	v_mov_b32_e32 v54, 0
	v_mov_b32_e32 v55, 0
	v_mov_b32_e32 v56, 0
	v_mov_b32_e32 v57, 0
	v_mov_b32_e32 v58, 0
	v_mov_b32_e32 v59, 0
.Lmg_h3:
	s_mov_b32 s17, 1
.Lmg_loop:
	s_add_i32 s0, s2, 2
	s_cmp_lt_i32 s0, s3
	s_cbranch_scc1 .Lmg_f0
	s_waitcnt vmcnt(0)
	s_branch .Lmg_c0
.Lmg_f0:
	s_cmp_eq_u32 s17, 1
	s_cbranch_scc1 .Lmg_g0
	s_waitcnt vmcnt(22)
	s_branch .Lmg_c0
.Lmg_g0:
	s_waitcnt vmcnt(18)
.Lmg_c0:
	s_and_b32 s0, s2, 0xfff
	s_cmp_lg_u32 s0, 0
	s_cbranch_scc1 .Lmg_nza
	v_mov_b32_e32 v44, 0
	v_mov_b32_e32 v52, 0
	v_mov_b32_e32 v45, 0
	v_mov_b32_e32 v53, 0
	v_mov_b32_e32 v46, 0
	v_mov_b32_e32 v54, 0
	v_mov_b32_e32 v47, 0
	v_mov_b32_e32 v55, 0
	v_mov_b32_e32 v48, 0
	v_mov_b32_e32 v56, 0
	v_mov_b32_e32 v49, 0
	v_mov_b32_e32 v57, 0
	v_mov_b32_e32 v50, 0
	v_mov_b32_e32 v58, 0
	v_mov_b32_e32 v51, 0
	v_mov_b32_e32 v59, 0
.Lmg_nza:
	v_max3_f32 v181, v60, v61, v62
	v_sub_f32_e32 v178, v60, v181
	v_sub_f32_e32 v179, v61, v181
	v_sub_f32_e32 v180, v62, v181
	v_exp_f32_e32 v178, v178
	v_exp_f32_e32 v179, v179
	v_exp_f32_e32 v180, v180
	v_lshlrev_b32_e32 v172, 16, v80
	v_and_b32_e32 v173, s9, v80
	v_lshlrev_b32_e32 v174, 16, v84
	v_and_b32_e32 v175, s9, v84
	v_mul_f32_e32 v148, v172, v174
	v_mul_f32_e32 v149, v173, v175
	v_lshlrev_b32_e32 v172, 16, v81
	v_and_b32_e32 v173, s9, v81
	v_lshlrev_b32_e32 v174, 16, v85
	v_and_b32_e32 v175, s9, v85
	v_mul_f32_e32 v150, v172, v174
	v_mul_f32_e32 v151, v173, v175
	v_lshlrev_b32_e32 v172, 16, v82
	v_and_b32_e32 v173, s9, v82
	v_lshlrev_b32_e32 v174, 16, v86
	v_and_b32_e32 v175, s9, v86
	v_mul_f32_e32 v152, v172, v174
	v_mul_f32_e32 v153, v173, v175
	v_lshlrev_b32_e32 v172, 16, v83
	v_and_b32_e32 v173, s9, v83
	v_lshlrev_b32_e32 v174, 16, v87
	v_and_b32_e32 v175, s9, v87
	v_mul_f32_e32 v154, v172, v174
	v_mul_f32_e32 v155, v173, v175
	v_add_f32_e32 v249, v178, v179
	v_add_f32_e32 v249, v249, v180
	v_rcp_f32_e32 v250, v249
	v_lshlrev_b32_e32 v172, 16, v76
	v_and_b32_e32 v173, s9, v76
	v_mul_f32_e32 v174, v4, v52
	v_fmac_f32_e32 v174, v12, v44
	v_fmac_f32_e32 v174, v20, v148
	v_mul_f32_e32 v164, v172, v174
	v_mul_f32_e32 v253, v164, v164
	v_mul_f32_e32 v175, v5, v53
	v_fmac_f32_e32 v175, v13, v45
	v_fmac_f32_e32 v175, v21, v149
	v_mul_f32_e32 v165, v173, v175
	v_fmac_f32_e32 v253, v165, v165
	v_lshlrev_b32_e32 v172, 16, v77
	v_and_b32_e32 v173, s9, v77
	v_mul_f32_e32 v174, v6, v54
	v_fmac_f32_e32 v174, v14, v46
	v_fmac_f32_e32 v174, v22, v150
	v_mul_f32_e32 v166, v172, v174
	v_fmac_f32_e32 v253, v166, v166
	v_mul_f32_e32 v175, v7, v55
	v_fmac_f32_e32 v175, v15, v47
	v_fmac_f32_e32 v175, v23, v151
	v_mul_f32_e32 v167, v173, v175
	v_fmac_f32_e32 v253, v167, v167
	v_lshlrev_b32_e32 v172, 16, v78
	v_and_b32_e32 v173, s9, v78
	v_mul_f32_e32 v174, v8, v56
	v_fmac_f32_e32 v174, v16, v48
	v_fmac_f32_e32 v174, v24, v152
	v_mul_f32_e32 v168, v172, v174
	v_fmac_f32_e32 v253, v168, v168
	v_mul_f32_e32 v175, v9, v57
	v_fmac_f32_e32 v175, v17, v49
	v_fmac_f32_e32 v175, v25, v153
	v_mul_f32_e32 v169, v173, v175
	v_fmac_f32_e32 v253, v169, v169
	v_lshlrev_b32_e32 v172, 16, v79
	v_and_b32_e32 v173, s9, v79
	v_mul_f32_e32 v174, v10, v58
	v_fmac_f32_e32 v174, v18, v50
	v_fmac_f32_e32 v174, v26, v154
	v_mul_f32_e32 v170, v172, v174
	v_fmac_f32_e32 v253, v170, v170
	v_mul_f32_e32 v175, v11, v59
	v_fmac_f32_e32 v175, v19, v51
	v_fmac_f32_e32 v175, v27, v155
	v_mul_f32_e32 v171, v173, v175
	v_fmac_f32_e32 v253, v171, v171
	v_fma_f32 v251, -v249, v250, 2.0
	v_mul_f32_e32 v250, v250, v251
	v_mul_f32_e32 v178, v178, v250
	v_mul_f32_e32 v179, v179, v250
	v_mul_f32_e32 v180, v180, v250
	v_mov_b32_e32 v52, v44
	v_mov_b32_e32 v53, v45
	v_mov_b32_e32 v54, v46
	v_mov_b32_e32 v55, v47
	v_mov_b32_e32 v56, v48
	v_mov_b32_e32 v57, v49
	v_mov_b32_e32 v58, v50
	v_mov_b32_e32 v59, v51
	v_mov_b32_e32 v44, v148
	v_mov_b32_e32 v45, v149
	v_mov_b32_e32 v46, v150
	v_mov_b32_e32 v47, v151
	v_mov_b32_e32 v48, v152
	v_mov_b32_e32 v49, v153
	v_mov_b32_e32 v50, v154
	v_mov_b32_e32 v51, v155
	v_lshlrev_b32_e32 v172, 16, v64
	v_and_b32_e32 v173, s9, v64
	v_lshlrev_b32_e32 v174, 16, v68
	v_and_b32_e32 v175, s9, v68
	v_lshlrev_b32_e32 v176, 16, v72
	v_and_b32_e32 v177, s9, v72
	v_mul_f32_e32 v156, v178, v172
	v_fmac_f32_e32 v156, v179, v174
	v_fmac_f32_e32 v156, v180, v176
	v_mul_f32_e32 v157, v178, v173
	v_fmac_f32_e32 v157, v179, v175
	v_fmac_f32_e32 v157, v180, v177
	v_mul_f32_e32 v252, v156, v156
	v_fmac_f32_e32 v252, v157, v157
	v_lshlrev_b32_e32 v172, 16, v65
	v_and_b32_e32 v173, s9, v65
	v_lshlrev_b32_e32 v174, 16, v69
	v_and_b32_e32 v175, s9, v69
	v_lshlrev_b32_e32 v176, 16, v73
	v_and_b32_e32 v177, s9, v73
	v_mul_f32_e32 v158, v178, v172
	v_fmac_f32_e32 v158, v179, v174
	v_fmac_f32_e32 v158, v180, v176
	v_mul_f32_e32 v159, v178, v173
	v_fmac_f32_e32 v159, v179, v175
	v_fmac_f32_e32 v159, v180, v177
	v_fmac_f32_e32 v252, v158, v158
	v_fmac_f32_e32 v252, v159, v159
	v_lshlrev_b32_e32 v172, 16, v66
	v_and_b32_e32 v173, s9, v66
	v_lshlrev_b32_e32 v174, 16, v70
	v_and_b32_e32 v175, s9, v70
	v_lshlrev_b32_e32 v176, 16, v74
	v_and_b32_e32 v177, s9, v74
	v_mul_f32_e32 v160, v178, v172
	v_fmac_f32_e32 v160, v179, v174
	v_fmac_f32_e32 v160, v180, v176
	v_mul_f32_e32 v161, v178, v173
	v_fmac_f32_e32 v161, v179, v175
	v_fmac_f32_e32 v161, v180, v177
	v_fmac_f32_e32 v252, v160, v160
	v_fmac_f32_e32 v252, v161, v161
	v_lshlrev_b32_e32 v172, 16, v67
	v_and_b32_e32 v173, s9, v67
	v_lshlrev_b32_e32 v174, 16, v71
	v_and_b32_e32 v175, s9, v71
	v_lshlrev_b32_e32 v176, 16, v75
	v_and_b32_e32 v177, s9, v75
	v_mul_f32_e32 v162, v178, v172
	v_fmac_f32_e32 v162, v179, v174
	v_fmac_f32_e32 v162, v180, v176
	v_mul_f32_e32 v163, v178, v173
	v_fmac_f32_e32 v163, v179, v175
	v_fmac_f32_e32 v163, v180, v177
	v_fmac_f32_e32 v252, v162, v162
	v_fmac_f32_e32 v252, v163, v163
	s_nop 1
	v_add_f32_dpp v252, v252, v252 quad_perm:[1,0,3,2] row_mask:0xf bank_mask:0xf
	v_add_f32_dpp v253, v253, v253 quad_perm:[1,0,3,2] row_mask:0xf bank_mask:0xf
	s_nop 0
	v_add_f32_dpp v252, v252, v252 quad_perm:[2,3,0,1] row_mask:0xf bank_mask:0xf
	v_add_f32_dpp v253, v253, v253 quad_perm:[2,3,0,1] row_mask:0xf bank_mask:0xf
	s_nop 0
	v_add_f32_dpp v252, v252, v252 row_ror:4 row_mask:0xf bank_mask:0xf
	v_add_f32_dpp v253, v253, v253 row_ror:4 row_mask:0xf bank_mask:0xf
	s_nop 0
	v_add_f32_dpp v252, v252, v252 row_ror:8 row_mask:0xf bank_mask:0xf
	v_add_f32_dpp v253, v253, v253 row_ror:8 row_mask:0xf bank_mask:0xf
	s_nop 0
	v_mov_b32_e32 v254, v252
	v_mov_b32_e32 v255, v253
	s_nop 1
	v_permlane16_swap_b32_e32 v252, v254
	v_permlane16_swap_b32_e32 v253, v255
	v_add_f32_e32 v252, v252, v254
	v_add_f32_e32 v253, v253, v255
	v_mov_b32_e32 v254, v252
	v_mov_b32_e32 v255, v253
	s_nop 1
	v_permlane32_swap_b32_e32 v252, v254
	v_permlane32_swap_b32_e32 v253, v255
	v_add_f32_e32 v252, v252, v254
	v_add_f32_e32 v253, v253, v255
	v_fma_f32 v252, v252, s31, v63
	v_fma_f32 v253, v253, s31, v63
	v_rsq_f32_e32 v140, v252
	v_rsq_f32_e32 v141, v253
	v_mul_f32_e32 v252, 0.5, v252
	v_mul_f32_e32 v253, 0.5, v253
	v_mul_f32_e32 v254, v140, v140
	v_mul_f32_e32 v255, v141, v141
	v_fma_f32 v254, -v252, v254, 0.5
	v_fma_f32 v255, -v253, v255, 0.5
	v_fmac_f32_e32 v140, v140, v254
	v_fmac_f32_e32 v141, v141, v255
	v_mul_f32_e32 v156, v156, v140
	v_mul_f32_e32 v164, v164, v141
	v_mul_f32_e32 v156, v156, v28
	v_mul_f32_e32 v164, v164, v36
	v_mul_f32_e32 v157, v157, v140
	v_mul_f32_e32 v165, v165, v141
	v_mul_f32_e32 v157, v157, v29
	v_mul_f32_e32 v165, v165, v37
	v_cvt_pk_bf16_f32 v148, v156, v157
	v_cvt_pk_bf16_f32 v152, v164, v165
	v_mul_f32_e32 v158, v158, v140
	v_mul_f32_e32 v166, v166, v141
	v_mul_f32_e32 v158, v158, v30
	v_mul_f32_e32 v166, v166, v38
	v_mul_f32_e32 v159, v159, v140
	v_mul_f32_e32 v167, v167, v141
	v_mul_f32_e32 v159, v159, v31
	v_mul_f32_e32 v167, v167, v39
	v_cvt_pk_bf16_f32 v149, v158, v159
	v_cvt_pk_bf16_f32 v153, v166, v167
	v_mul_f32_e32 v160, v160, v140
	v_mul_f32_e32 v168, v168, v141
	v_mul_f32_e32 v160, v160, v32
	v_mul_f32_e32 v168, v168, v40
	v_mul_f32_e32 v161, v161, v140
	v_mul_f32_e32 v169, v169, v141
	v_mul_f32_e32 v161, v161, v33
	v_mul_f32_e32 v169, v169, v41
	v_cvt_pk_bf16_f32 v150, v160, v161
	v_cvt_pk_bf16_f32 v154, v168, v169
	v_mul_f32_e32 v162, v162, v140
	v_mul_f32_e32 v170, v170, v141
	v_mul_f32_e32 v162, v162, v34
	v_mul_f32_e32 v170, v170, v42
	v_mul_f32_e32 v163, v163, v140
	v_mul_f32_e32 v171, v171, v141
	v_mul_f32_e32 v163, v163, v35
	v_mul_f32_e32 v171, v171, v43
	v_cvt_pk_bf16_f32 v151, v162, v163
	v_cvt_pk_bf16_f32 v155, v170, v171
	global_store_dwordx4 v0, v[148:151], s[28:29]
	global_store_dwordx4 v0, v[152:155], s[28:29] offset:1024
	s_add_u32 s28, s28, 0x800
	s_addc_u32 s29, s29, 0
	s_cmp_lt_i32 s30, s3
	s_cbranch_scc0 .Lmg_nl0
	global_load_dword v60, v1, s[4:5] nt
	global_load_dword v61, v1, s[10:11] nt
	global_load_dword v62, v1, s[14:15] nt
	global_load_dwordx4 v[64:67], v0, s[18:19] nt
	global_load_dwordx4 v[68:71], v0, s[20:21] nt
	global_load_dwordx4 v[72:75], v0, s[22:23] nt
	global_load_dwordx4 v[76:79], v0, s[26:27]
	global_load_dwordx4 v[80:83], v0, s[26:27] offset:1024
	global_load_dwordx4 v[84:87], v0, s[26:27] offset:2048
	s_add_u32 s4, s4, 32
	s_addc_u32 s5, s5, 0
	s_add_u32 s10, s10, 32
	s_addc_u32 s11, s11, 0
	s_add_u32 s14, s14, 32
	s_addc_u32 s15, s15, 0
	s_add_u32 s18, s18, 0x400
	s_addc_u32 s19, s19, 0
	s_add_u32 s20, s20, 0x400
	s_addc_u32 s21, s21, 0
	s_add_u32 s22, s22, 0x400
	s_addc_u32 s23, s23, 0
	s_add_u32 s26, s26, 0xc00
	s_addc_u32 s27, s27, 0
	s_add_i32 s30, s30, 1
.Lmg_nl0:
	s_add_i32 s2, s2, 1
	s_cmp_lt_i32 s2, s3
	s_cbranch_scc0 .LBB0_363
	s_add_i32 s0, s2, 2
	s_cmp_lt_i32 s0, s3
	s_cbranch_scc1 .Lmg_f1
	s_waitcnt vmcnt(0)
	s_branch .Lmg_c1

.Lmg_nzb:
	v_max3_f32 v181, v88, v89, v90
	v_sub_f32_e32 v178, v88, v181
	v_sub_f32_e32 v179, v89, v181
	v_sub_f32_e32 v180, v90, v181
	v_exp_f32_e32 v178, v178
	v_exp_f32_e32 v179, v179
	v_exp_f32_e32 v180, v180
	v_lshlrev_b32_e32 v172, 16, v108
	v_and_b32_e32 v173, s9, v108
	v_lshlrev_b32_e32 v174, 16, v112
	v_and_b32_e32 v175, s9, v112
	v_mul_f32_e32 v148, v172, v174
	v_mul_f32_e32 v149, v173, v175
	v_lshlrev_b32_e32 v172, 16, v109
	v_and_b32_e32 v173, s9, v109
	v_lshlrev_b32_e32 v174, 16, v113
	v_and_b32_e32 v175, s9, v113
	v_mul_f32_e32 v150, v172, v174
	v_mul_f32_e32 v151, v173, v175
	v_lshlrev_b32_e32 v172, 16, v110
	v_and_b32_e32 v173, s9, v110
	v_lshlrev_b32_e32 v174, 16, v114
	v_and_b32_e32 v175, s9, v114
	v_mul_f32_e32 v152, v172, v174
	v_mul_f32_e32 v153, v173, v175
	v_lshlrev_b32_e32 v172, 16, v111
	v_and_b32_e32 v173, s9, v111
	v_lshlrev_b32_e32 v174, 16, v115
	v_and_b32_e32 v175, s9, v115
	v_mul_f32_e32 v154, v172, v174
	v_mul_f32_e32 v155, v173, v175
	v_add_f32_e32 v249, v178, v179
	v_add_f32_e32 v249, v249, v180
	v_rcp_f32_e32 v250, v249
	v_lshlrev_b32_e32 v172, 16, v104
	v_and_b32_e32 v173, s9, v104
	v_mul_f32_e32 v174, v4, v52
	v_fmac_f32_e32 v174, v12, v44
	v_fmac_f32_e32 v174, v20, v148
	v_mul_f32_e32 v164, v172, v174
	v_mul_f32_e32 v253, v164, v164
	v_mul_f32_e32 v175, v5, v53
	v_fmac_f32_e32 v175, v13, v45
	v_fmac_f32_e32 v175, v21, v149
	v_mul_f32_e32 v165, v173, v175
	v_fmac_f32_e32 v253, v165, v165
	v_lshlrev_b32_e32 v172, 16, v105
	v_and_b32_e32 v173, s9, v105
	v_mul_f32_e32 v174, v6, v54
	v_fmac_f32_e32 v174, v14, v46
	v_fmac_f32_e32 v174, v22, v150
	v_mul_f32_e32 v166, v172, v174
	v_fmac_f32_e32 v253, v166, v166
	v_mul_f32_e32 v175, v7, v55
	v_fmac_f32_e32 v175, v15, v47
	v_fmac_f32_e32 v175, v23, v151
	v_mul_f32_e32 v167, v173, v175
	v_fmac_f32_e32 v253, v167, v167
	v_lshlrev_b32_e32 v172, 16, v106
	v_and_b32_e32 v173, s9, v106
	v_mul_f32_e32 v174, v8, v56
	v_fmac_f32_e32 v174, v16, v48
	v_fmac_f32_e32 v174, v24, v152
	v_mul_f32_e32 v168, v172, v174
	v_fmac_f32_e32 v253, v168, v168
	v_mul_f32_e32 v175, v9, v57
	v_fmac_f32_e32 v175, v17, v49
	v_fmac_f32_e32 v175, v25, v153
	v_mul_f32_e32 v169, v173, v175
	v_fmac_f32_e32 v253, v169, v169
	v_lshlrev_b32_e32 v172, 16, v107
	v_and_b32_e32 v173, s9, v107
	v_mul_f32_e32 v174, v10, v58
	v_fmac_f32_e32 v174, v18, v50
	v_fmac_f32_e32 v174, v26, v154
	v_mul_f32_e32 v170, v172, v174
	v_fmac_f32_e32 v253, v170, v170
	v_mul_f32_e32 v175, v11, v59
	v_fmac_f32_e32 v175, v19, v51
	v_fmac_f32_e32 v175, v27, v155
	v_mul_f32_e32 v171, v173, v175
	v_fmac_f32_e32 v253, v171, v171
	v_fma_f32 v251, -v249, v250, 2.0
	v_mul_f32_e32 v250, v250, v251
	v_mul_f32_e32 v178, v178, v250
	v_mul_f32_e32 v179, v179, v250
	v_mul_f32_e32 v180, v180, v250
	v_mov_b32_e32 v52, v44
	v_mov_b32_e32 v53, v45
	v_mov_b32_e32 v54, v46
	v_mov_b32_e32 v55, v47
	v_mov_b32_e32 v56, v48
	v_mov_b32_e32 v57, v49
	v_mov_b32_e32 v58, v50
	v_mov_b32_e32 v59, v51
	v_mov_b32_e32 v44, v148
	v_mov_b32_e32 v45, v149
	v_mov_b32_e32 v46, v150
	v_mov_b32_e32 v47, v151
	v_mov_b32_e32 v48, v152
	v_mov_b32_e32 v49, v153
	v_mov_b32_e32 v50, v154
	v_mov_b32_e32 v51, v155
	v_lshlrev_b32_e32 v172, 16, v92
	v_and_b32_e32 v173, s9, v92
	v_lshlrev_b32_e32 v174, 16, v96
	v_and_b32_e32 v175, s9, v96
	v_lshlrev_b32_e32 v176, 16, v100
	v_and_b32_e32 v177, s9, v100
	v_mul_f32_e32 v156, v178, v172
	v_fmac_f32_e32 v156, v179, v174
	v_fmac_f32_e32 v156, v180, v176
	v_mul_f32_e32 v157, v178, v173
	v_fmac_f32_e32 v157, v179, v175
	v_fmac_f32_e32 v157, v180, v177
	v_mul_f32_e32 v252, v156, v156
	v_fmac_f32_e32 v252, v157, v157
	v_lshlrev_b32_e32 v172, 16, v93
	v_and_b32_e32 v173, s9, v93
	v_lshlrev_b32_e32 v174, 16, v97
	v_and_b32_e32 v175, s9, v97
	v_lshlrev_b32_e32 v176, 16, v101
	v_and_b32_e32 v177, s9, v101
	v_mul_f32_e32 v158, v178, v172
	v_fmac_f32_e32 v158, v179, v174
	v_fmac_f32_e32 v158, v180, v176
	v_mul_f32_e32 v159, v178, v173
	v_fmac_f32_e32 v159, v179, v175
	v_fmac_f32_e32 v159, v180, v177
	v_fmac_f32_e32 v252, v158, v158
	v_fmac_f32_e32 v252, v159, v159
	v_lshlrev_b32_e32 v172, 16, v94
	v_and_b32_e32 v173, s9, v94
	v_lshlrev_b32_e32 v174, 16, v98
	v_and_b32_e32 v175, s9, v98
	v_lshlrev_b32_e32 v176, 16, v102
	v_and_b32_e32 v177, s9, v102
	v_mul_f32_e32 v160, v178, v172
	v_fmac_f32_e32 v160, v179, v174
	v_fmac_f32_e32 v160, v180, v176
	v_mul_f32_e32 v161, v178, v173
	v_fmac_f32_e32 v161, v179, v175
	v_fmac_f32_e32 v161, v180, v177
	v_fmac_f32_e32 v252, v160, v160
	v_fmac_f32_e32 v252, v161, v161
	v_lshlrev_b32_e32 v172, 16, v95
	v_and_b32_e32 v173, s9, v95
	v_lshlrev_b32_e32 v174, 16, v99
	v_and_b32_e32 v175, s9, v99
	v_lshlrev_b32_e32 v176, 16, v103
	v_and_b32_e32 v177, s9, v103
	v_mul_f32_e32 v162, v178, v172
	v_fmac_f32_e32 v162, v179, v174
	v_fmac_f32_e32 v162, v180, v176
	v_mul_f32_e32 v163, v178, v173
	v_fmac_f32_e32 v163, v179, v175
	v_fmac_f32_e32 v163, v180, v177
	v_fmac_f32_e32 v252, v162, v162
	v_fmac_f32_e32 v252, v163, v163
	s_nop 1
	v_add_f32_dpp v252, v252, v252 quad_perm:[1,0,3,2] row_mask:0xf bank_mask:0xf
	v_add_f32_dpp v253, v253, v253 quad_perm:[1,0,3,2] row_mask:0xf bank_mask:0xf
	s_nop 0
	v_add_f32_dpp v252, v252, v252 quad_perm:[2,3,0,1] row_mask:0xf bank_mask:0xf
	v_add_f32_dpp v253, v253, v253 quad_perm:[2,3,0,1] row_mask:0xf bank_mask:0xf
	s_nop 0
	v_add_f32_dpp v252, v252, v252 row_ror:4 row_mask:0xf bank_mask:0xf
	v_add_f32_dpp v253, v253, v253 row_ror:4 row_mask:0xf bank_mask:0xf
	s_nop 0
	v_add_f32_dpp v252, v252, v252 row_ror:8 row_mask:0xf bank_mask:0xf
	v_add_f32_dpp v253, v253, v253 row_ror:8 row_mask:0xf bank_mask:0xf
	s_nop 0
	v_mov_b32_e32 v254, v252
	v_mov_b32_e32 v255, v253
	s_nop 1
	v_permlane16_swap_b32_e32 v252, v254
	v_permlane16_swap_b32_e32 v253, v255
	v_add_f32_e32 v252, v252, v254
	v_add_f32_e32 v253, v253, v255
	v_mov_b32_e32 v254, v252
	v_mov_b32_e32 v255, v253
	s_nop 1
	v_permlane32_swap_b32_e32 v252, v254
	v_permlane32_swap_b32_e32 v253, v255
	v_add_f32_e32 v252, v252, v254
	v_add_f32_e32 v253, v253, v255
	v_fma_f32 v252, v252, s31, v63
	v_fma_f32 v253, v253, s31, v63
	v_rsq_f32_e32 v140, v252
	v_rsq_f32_e32 v141, v253
	v_mul_f32_e32 v252, 0.5, v252
	v_mul_f32_e32 v253, 0.5, v253
	v_mul_f32_e32 v254, v140, v140
	v_mul_f32_e32 v255, v141, v141
	v_fma_f32 v254, -v252, v254, 0.5
	v_fma_f32 v255, -v253, v255, 0.5
	v_fmac_f32_e32 v140, v140, v254
	v_fmac_f32_e32 v141, v141, v255
	v_mul_f32_e32 v156, v156, v140
	v_mul_f32_e32 v164, v164, v141
	v_mul_f32_e32 v156, v156, v28
	v_mul_f32_e32 v164, v164, v36
	v_mul_f32_e32 v157, v157, v140
	v_mul_f32_e32 v165, v165, v141
	v_mul_f32_e32 v157, v157, v29
	v_mul_f32_e32 v165, v165, v37
	v_cvt_pk_bf16_f32 v148, v156, v157
	v_cvt_pk_bf16_f32 v152, v164, v165
	v_mul_f32_e32 v158, v158, v140
	v_mul_f32_e32 v166, v166, v141
	v_mul_f32_e32 v158, v158, v30
	v_mul_f32_e32 v166, v166, v38
	v_mul_f32_e32 v159, v159, v140
	v_mul_f32_e32 v167, v167, v141
	v_mul_f32_e32 v159, v159, v31
	v_mul_f32_e32 v167, v167, v39
	v_cvt_pk_bf16_f32 v149, v158, v159
	v_cvt_pk_bf16_f32 v153, v166, v167
	v_mul_f32_e32 v160, v160, v140
	v_mul_f32_e32 v168, v168, v141
	v_mul_f32_e32 v160, v160, v32
	v_mul_f32_e32 v168, v168, v40
	v_mul_f32_e32 v161, v161, v140
	v_mul_f32_e32 v169, v169, v141
	v_mul_f32_e32 v161, v161, v33
	v_mul_f32_e32 v169, v169, v41
	v_cvt_pk_bf16_f32 v150, v160, v161
	v_cvt_pk_bf16_f32 v154, v168, v169
	v_mul_f32_e32 v162, v162, v140
	v_mul_f32_e32 v170, v170, v141
	v_mul_f32_e32 v162, v162, v34
	v_mul_f32_e32 v170, v170, v42
	v_mul_f32_e32 v163, v163, v140
	v_mul_f32_e32 v171, v171, v141
	v_mul_f32_e32 v163, v163, v35
	v_mul_f32_e32 v171, v171, v43
	v_cvt_pk_bf16_f32 v151, v162, v163
	v_cvt_pk_bf16_f32 v155, v170, v171
	global_store_dwordx4 v0, v[148:151], s[28:29]
	global_store_dwordx4 v0, v[152:155], s[28:29] offset:1024
	s_add_u32 s28, s28, 0x800
	s_addc_u32 s29, s29, 0
	s_cmp_lt_i32 s30, s3
	s_cbranch_scc0 .Lmg_nl1
	global_load_dword v88, v1, s[4:5] nt
	global_load_dword v89, v1, s[10:11] nt
	global_load_dword v90, v1, s[14:15] nt
	global_load_dwordx4 v[92:95], v0, s[18:19] nt
	global_load_dwordx4 v[96:99], v0, s[20:21] nt
	global_load_dwordx4 v[100:103], v0, s[22:23] nt
	global_load_dwordx4 v[104:107], v0, s[26:27]
	global_load_dwordx4 v[108:111], v0, s[26:27] offset:1024
	global_load_dwordx4 v[112:115], v0, s[26:27] offset:2048
	s_add_u32 s4, s4, 32
	s_addc_u32 s5, s5, 0
	s_add_u32 s10, s10, 32
	s_addc_u32 s11, s11, 0
	s_add_u32 s14, s14, 32
	s_addc_u32 s15, s15, 0
	s_add_u32 s18, s18, 0x400
	s_addc_u32 s19, s19, 0
	s_add_u32 s20, s20, 0x400
	s_addc_u32 s21, s21, 0
	s_add_u32 s22, s22, 0x400
	s_addc_u32 s23, s23, 0
	s_add_u32 s26, s26, 0xc00
	s_addc_u32 s27, s27, 0
	s_add_i32 s30, s30, 1

.Lmg_f2:
	s_waitcnt vmcnt(22)

.Lmg_nzc:
	v_max3_f32 v181, v116, v117, v118
	v_sub_f32_e32 v178, v116, v181
	v_sub_f32_e32 v179, v117, v181
	v_sub_f32_e32 v180, v118, v181
	v_exp_f32_e32 v178, v178
	v_exp_f32_e32 v179, v179
	v_exp_f32_e32 v180, v180
	v_lshlrev_b32_e32 v172, 16, v136
	v_and_b32_e32 v173, s9, v136
	v_lshlrev_b32_e32 v174, 16, v144
	v_and_b32_e32 v175, s9, v144
	v_mul_f32_e32 v148, v172, v174
	v_mul_f32_e32 v149, v173, v175
	v_lshlrev_b32_e32 v172, 16, v137
	v_and_b32_e32 v173, s9, v137
	v_lshlrev_b32_e32 v174, 16, v145
	v_and_b32_e32 v175, s9, v145
	v_mul_f32_e32 v150, v172, v174
	v_mul_f32_e32 v151, v173, v175
	v_lshlrev_b32_e32 v172, 16, v138
	v_and_b32_e32 v173, s9, v138
	v_lshlrev_b32_e32 v174, 16, v146
	v_and_b32_e32 v175, s9, v146
	v_mul_f32_e32 v152, v172, v174
	v_mul_f32_e32 v153, v173, v175
	v_lshlrev_b32_e32 v172, 16, v139
	v_and_b32_e32 v173, s9, v139
	v_lshlrev_b32_e32 v174, 16, v147
	v_and_b32_e32 v175, s9, v147
	v_mul_f32_e32 v154, v172, v174
	v_mul_f32_e32 v155, v173, v175
	v_add_f32_e32 v249, v178, v179
	v_add_f32_e32 v249, v249, v180
	v_rcp_f32_e32 v250, v249
	v_lshlrev_b32_e32 v172, 16, v132
	v_and_b32_e32 v173, s9, v132
	v_mul_f32_e32 v174, v4, v52
	v_fmac_f32_e32 v174, v12, v44
	v_fmac_f32_e32 v174, v20, v148
	v_mul_f32_e32 v164, v172, v174
	v_mul_f32_e32 v253, v164, v164
	v_mul_f32_e32 v175, v5, v53
	v_fmac_f32_e32 v175, v13, v45
	v_fmac_f32_e32 v175, v21, v149
	v_mul_f32_e32 v165, v173, v175
	v_fmac_f32_e32 v253, v165, v165
	v_lshlrev_b32_e32 v172, 16, v133
	v_and_b32_e32 v173, s9, v133
	v_mul_f32_e32 v174, v6, v54
	v_fmac_f32_e32 v174, v14, v46
	v_fmac_f32_e32 v174, v22, v150
	v_mul_f32_e32 v166, v172, v174
	v_fmac_f32_e32 v253, v166, v166
	v_mul_f32_e32 v175, v7, v55
	v_fmac_f32_e32 v175, v15, v47
	v_fmac_f32_e32 v175, v23, v151
	v_mul_f32_e32 v167, v173, v175
	v_fmac_f32_e32 v253, v167, v167
	v_lshlrev_b32_e32 v172, 16, v134
	v_and_b32_e32 v173, s9, v134
	v_mul_f32_e32 v174, v8, v56
	v_fmac_f32_e32 v174, v16, v48
	v_fmac_f32_e32 v174, v24, v152
	v_mul_f32_e32 v168, v172, v174
	v_fmac_f32_e32 v253, v168, v168
	v_mul_f32_e32 v175, v9, v57
	v_fmac_f32_e32 v175, v17, v49
	v_fmac_f32_e32 v175, v25, v153
	v_mul_f32_e32 v169, v173, v175
	v_fmac_f32_e32 v253, v169, v169
	v_lshlrev_b32_e32 v172, 16, v135
	v_and_b32_e32 v173, s9, v135
	v_mul_f32_e32 v174, v10, v58
	v_fmac_f32_e32 v174, v18, v50
	v_fmac_f32_e32 v174, v26, v154
	v_mul_f32_e32 v170, v172, v174
	v_fmac_f32_e32 v253, v170, v170
	v_mul_f32_e32 v175, v11, v59
	v_fmac_f32_e32 v175, v19, v51
	v_fmac_f32_e32 v175, v27, v155
	v_mul_f32_e32 v171, v173, v175
	v_fmac_f32_e32 v253, v171, v171
	v_fma_f32 v251, -v249, v250, 2.0
	v_mul_f32_e32 v250, v250, v251
	v_mul_f32_e32 v178, v178, v250
	v_mul_f32_e32 v179, v179, v250
	v_mul_f32_e32 v180, v180, v250
	v_mov_b32_e32 v52, v44
	v_mov_b32_e32 v53, v45
	v_mov_b32_e32 v54, v46
	v_mov_b32_e32 v55, v47
	v_mov_b32_e32 v56, v48
	v_mov_b32_e32 v57, v49
	v_mov_b32_e32 v58, v50
	v_mov_b32_e32 v59, v51
	v_mov_b32_e32 v44, v148
	v_mov_b32_e32 v45, v149
	v_mov_b32_e32 v46, v150
	v_mov_b32_e32 v47, v151
	v_mov_b32_e32 v48, v152
	v_mov_b32_e32 v49, v153
	v_mov_b32_e32 v50, v154
	v_mov_b32_e32 v51, v155
	v_lshlrev_b32_e32 v172, 16, v120
	v_and_b32_e32 v173, s9, v120
	v_lshlrev_b32_e32 v174, 16, v124
	v_and_b32_e32 v175, s9, v124
	v_lshlrev_b32_e32 v176, 16, v128
	v_and_b32_e32 v177, s9, v128
	v_mul_f32_e32 v156, v178, v172
	v_fmac_f32_e32 v156, v179, v174
	v_fmac_f32_e32 v156, v180, v176
	v_mul_f32_e32 v157, v178, v173
	v_fmac_f32_e32 v157, v179, v175
	v_fmac_f32_e32 v157, v180, v177
	v_mul_f32_e32 v252, v156, v156
	v_fmac_f32_e32 v252, v157, v157
	v_lshlrev_b32_e32 v172, 16, v121
	v_and_b32_e32 v173, s9, v121
	v_lshlrev_b32_e32 v174, 16, v125
	v_and_b32_e32 v175, s9, v125
	v_lshlrev_b32_e32 v176, 16, v129
	v_and_b32_e32 v177, s9, v129
	v_mul_f32_e32 v158, v178, v172
	v_fmac_f32_e32 v158, v179, v174
	v_fmac_f32_e32 v158, v180, v176
	v_mul_f32_e32 v159, v178, v173
	v_fmac_f32_e32 v159, v179, v175
	v_fmac_f32_e32 v159, v180, v177
	v_fmac_f32_e32 v252, v158, v158
	v_fmac_f32_e32 v252, v159, v159
	v_lshlrev_b32_e32 v172, 16, v122
	v_and_b32_e32 v173, s9, v122
	v_lshlrev_b32_e32 v174, 16, v126
	v_and_b32_e32 v175, s9, v126
	v_lshlrev_b32_e32 v176, 16, v130
	v_and_b32_e32 v177, s9, v130
	v_mul_f32_e32 v160, v178, v172
	v_fmac_f32_e32 v160, v179, v174
	v_fmac_f32_e32 v160, v180, v176
	v_mul_f32_e32 v161, v178, v173
	v_fmac_f32_e32 v161, v179, v175
	v_fmac_f32_e32 v161, v180, v177
	v_fmac_f32_e32 v252, v160, v160
	v_fmac_f32_e32 v252, v161, v161
	v_lshlrev_b32_e32 v172, 16, v123
	v_and_b32_e32 v173, s9, v123
	v_lshlrev_b32_e32 v174, 16, v127
	v_and_b32_e32 v175, s9, v127
	v_lshlrev_b32_e32 v176, 16, v131
	v_and_b32_e32 v177, s9, v131
	v_mul_f32_e32 v162, v178, v172
	v_fmac_f32_e32 v162, v179, v174
	v_fmac_f32_e32 v162, v180, v176
	v_mul_f32_e32 v163, v178, v173
	v_fmac_f32_e32 v163, v179, v175
	v_fmac_f32_e32 v163, v180, v177
	v_fmac_f32_e32 v252, v162, v162
	v_fmac_f32_e32 v252, v163, v163
	s_nop 1
	v_add_f32_dpp v252, v252, v252 quad_perm:[1,0,3,2] row_mask:0xf bank_mask:0xf
	v_add_f32_dpp v253, v253, v253 quad_perm:[1,0,3,2] row_mask:0xf bank_mask:0xf
	s_nop 0
	v_add_f32_dpp v252, v252, v252 quad_perm:[2,3,0,1] row_mask:0xf bank_mask:0xf
	v_add_f32_dpp v253, v253, v253 quad_perm:[2,3,0,1] row_mask:0xf bank_mask:0xf
	s_nop 0
	v_add_f32_dpp v252, v252, v252 row_ror:4 row_mask:0xf bank_mask:0xf
	v_add_f32_dpp v253, v253, v253 row_ror:4 row_mask:0xf bank_mask:0xf
	s_nop 0
	v_add_f32_dpp v252, v252, v252 row_ror:8 row_mask:0xf bank_mask:0xf
	v_add_f32_dpp v253, v253, v253 row_ror:8 row_mask:0xf bank_mask:0xf
	s_nop 0
	v_mov_b32_e32 v254, v252
	v_mov_b32_e32 v255, v253
	s_nop 1
	v_permlane16_swap_b32_e32 v252, v254
	v_permlane16_swap_b32_e32 v253, v255
	v_add_f32_e32 v252, v252, v254
	v_add_f32_e32 v253, v253, v255
	v_mov_b32_e32 v254, v252
	v_mov_b32_e32 v255, v253
	s_nop 1
	v_permlane32_swap_b32_e32 v252, v254
	v_permlane32_swap_b32_e32 v253, v255
	v_add_f32_e32 v252, v252, v254
	v_add_f32_e32 v253, v253, v255
	v_fma_f32 v252, v252, s31, v63
	v_fma_f32 v253, v253, s31, v63
	v_rsq_f32_e32 v140, v252
	v_rsq_f32_e32 v141, v253
	v_mul_f32_e32 v252, 0.5, v252
	v_mul_f32_e32 v253, 0.5, v253
	v_mul_f32_e32 v254, v140, v140
	v_mul_f32_e32 v255, v141, v141
	v_fma_f32 v254, -v252, v254, 0.5
	v_fma_f32 v255, -v253, v255, 0.5
	v_fmac_f32_e32 v140, v140, v254
	v_fmac_f32_e32 v141, v141, v255
	v_mul_f32_e32 v156, v156, v140
	v_mul_f32_e32 v164, v164, v141
	v_mul_f32_e32 v156, v156, v28
	v_mul_f32_e32 v164, v164, v36
	v_mul_f32_e32 v157, v157, v140
	v_mul_f32_e32 v165, v165, v141
	v_mul_f32_e32 v157, v157, v29
	v_mul_f32_e32 v165, v165, v37
	v_cvt_pk_bf16_f32 v148, v156, v157
	v_cvt_pk_bf16_f32 v152, v164, v165
	v_mul_f32_e32 v158, v158, v140
	v_mul_f32_e32 v166, v166, v141
	v_mul_f32_e32 v158, v158, v30
	v_mul_f32_e32 v166, v166, v38
	v_mul_f32_e32 v159, v159, v140
	v_mul_f32_e32 v167, v167, v141
	v_mul_f32_e32 v159, v159, v31
	v_mul_f32_e32 v167, v167, v39
	v_cvt_pk_bf16_f32 v149, v158, v159
	v_cvt_pk_bf16_f32 v153, v166, v167
	v_mul_f32_e32 v160, v160, v140
	v_mul_f32_e32 v168, v168, v141
	v_mul_f32_e32 v160, v160, v32
	v_mul_f32_e32 v168, v168, v40
	v_mul_f32_e32 v161, v161, v140
	v_mul_f32_e32 v169, v169, v141
	v_mul_f32_e32 v161, v161, v33
	v_mul_f32_e32 v169, v169, v41
	v_cvt_pk_bf16_f32 v150, v160, v161
	v_cvt_pk_bf16_f32 v154, v168, v169
	v_mul_f32_e32 v162, v162, v140
	v_mul_f32_e32 v170, v170, v141
	v_mul_f32_e32 v162, v162, v34
	v_mul_f32_e32 v170, v170, v42
	v_mul_f32_e32 v163, v163, v140
	v_mul_f32_e32 v171, v171, v141
	v_mul_f32_e32 v163, v163, v35
	v_mul_f32_e32 v171, v171, v43
	v_cvt_pk_bf16_f32 v151, v162, v163
	v_cvt_pk_bf16_f32 v155, v170, v171
	global_store_dwordx4 v0, v[148:151], s[28:29]
	global_store_dwordx4 v0, v[152:155], s[28:29] offset:1024
	s_add_u32 s28, s28, 0x800
	s_addc_u32 s29, s29, 0
	s_cmp_lt_i32 s30, s3
	s_cbranch_scc0 .Lmg_nl2
	global_load_dword v116, v1, s[4:5] nt
	global_load_dword v117, v1, s[10:11] nt
	global_load_dword v118, v1, s[14:15] nt
	global_load_dwordx4 v[120:123], v0, s[18:19] nt
	global_load_dwordx4 v[124:127], v0, s[20:21] nt
	global_load_dwordx4 v[128:131], v0, s[22:23] nt
	global_load_dwordx4 v[132:135], v0, s[26:27]
	global_load_dwordx4 v[136:139], v0, s[26:27] offset:1024
	global_load_dwordx4 v[144:147], v0, s[26:27] offset:2048
	s_add_u32 s4, s4, 32
	s_addc_u32 s5, s5, 0
	s_add_u32 s10, s10, 32
	s_addc_u32 s11, s11, 0
	s_add_u32 s14, s14, 32
	s_addc_u32 s15, s15, 0
	s_add_u32 s18, s18, 0x400
	s_addc_u32 s19, s19, 0
	s_add_u32 s20, s20, 0x400
	s_addc_u32 s21, s21, 0
	s_add_u32 s22, s22, 0x400
	s_addc_u32 s23, s23, 0
	s_add_u32 s26, s26, 0xc00
	s_addc_u32 s27, s27, 0
	s_add_i32 s30, s30, 1
.Lmg_nl2:
	s_add_i32 s2, s2, 1
	s_cmp_lt_i32 s2, s3
	s_mov_b32 s17, 0
	s_cbranch_scc1 .Lmg_loop

	.amdhsa_kernel _Z4mega4Args
		.amdhsa_group_segment_fixed_size 0
		.amdhsa_private_segment_fixed_size 0
		.amdhsa_kernarg_size 416
		.amdhsa_user_sgpr_count 2
		.amdhsa_user_sgpr_dispatch_ptr 0
		.amdhsa_user_sgpr_queue_ptr 0
		.amdhsa_user_sgpr_kernarg_segment_ptr 1
		.amdhsa_user_sgpr_dispatch_id 0
		.amdhsa_user_sgpr_kernarg_preload_length 0
		.amdhsa_user_sgpr_kernarg_preload_offset 0
		.amdhsa_user_sgpr_private_segment_size 0
		.amdhsa_uses_dynamic_stack 0
		.amdhsa_enable_private_segment 0
		.amdhsa_system_sgpr_workgroup_id_x 1
		.amdhsa_system_sgpr_workgroup_id_y 0
		.amdhsa_system_sgpr_workgroup_id_z 0
		.amdhsa_system_sgpr_workgroup_info 0
		.amdhsa_system_vgpr_workitem_id 2
		.amdhsa_next_free_vgpr 256
		.amdhsa_next_free_sgpr 98
		.amdhsa_accum_offset 256
		.amdhsa_reserve_vcc 1
		.amdhsa_float_round_mode_32 0
		.amdhsa_float_round_mode_16_64 0
		.amdhsa_float_denorm_mode_32 3
		.amdhsa_float_denorm_mode_16_64 3
		.amdhsa_dx10_clamp 1
		.amdhsa_ieee_mode 1
		.amdhsa_fp16_overflow 0
		.amdhsa_tg_split 0
		.amdhsa_exception_fp_ieee_invalid_op 0
		.amdhsa_exception_fp_denorm_src 0
		.amdhsa_exception_fp_ieee_div_zero 0
		.amdhsa_exception_fp_ieee_overflow 0
		.amdhsa_exception_fp_ieee_underflow 0
		.amdhsa_exception_fp_ieee_inexact 0
		.amdhsa_exception_int_div_zero 0
	.end_amdhsa_kernel

amdhsa.kernels:
  - .agpr_count:     0
    .args:
      - .offset:         0
        .size:           160
        .value_kind:     by_value
      - .offset:         160
        .size:           4
        .value_kind:     hidden_block_count_x
      - .offset:         164
        .size:           4
        .value_kind:     hidden_block_count_y
      - .offset:         168
        .size:           4
        .value_kind:     hidden_block_count_z
      - .offset:         172
        .size:           2
        .value_kind:     hidden_group_size_x
      - .offset:         174
        .size:           2
        .value_kind:     hidden_group_size_y
      - .offset:         176
        .size:           2
        .value_kind:     hidden_group_size_z
      - .offset:         178
        .size:           2
        .value_kind:     hidden_remainder_x
      - .offset:         180
        .size:           2
        .value_kind:     hidden_remainder_y
      - .offset:         182
        .size:           2
        .value_kind:     hidden_remainder_z
      - .offset:         200
        .size:           8
        .value_kind:     hidden_global_offset_x
      - .offset:         208
        .size:           8
        .value_kind:     hidden_global_offset_y
      - .offset:         216
        .size:           8
        .value_kind:     hidden_global_offset_z
      - .offset:         224
        .size:           2
        .value_kind:     hidden_grid_dims
      - .offset:         248
        .size:           8
        .value_kind:     hidden_multigrid_sync_arg
      - .offset:         280
        .size:           4
        .value_kind:     hidden_dynamic_lds_size
    .group_segment_fixed_size: 0
    .kernarg_segment_align: 8
    .kernarg_segment_size: 416
    .language:       OpenCL C
    .language_version:
      - 2
      - 0
    .max_flat_workgroup_size: 512
    .name:           _Z4mega4Args
    .private_segment_fixed_size: 0
    .sgpr_count:     104
    .sgpr_spill_count: 64
    .symbol:         _Z4mega4Args.kd
    .uniform_work_group_size: 1
    .uses_dynamic_stack: false
    .vgpr_count:     256
    .vgpr_spill_count: 0
    .wavefront_size: 64
